# GEMM loops: priority flips swapped (load segment s_setprio 1, MFMA block s_setprio 0)
# baseline (speedup 1.0000x reference)
.LBB0_159:
	ds_read_b128 v[150:153], v147
	ds_read_b128 v[154:157], v147 offset:1024
	ds_read_b128 v[158:161], v147 offset:2048
	ds_read_b128 v[162:165], v147 offset:3072
	ds_read_b128 v[166:169], v148
	ds_read_b128 v[170:173], v148 offset:1024
	ds_read_b128 v[174:177], v148 offset:2048
	ds_read_b128 v[178:181], v148 offset:3072
	s_add_u32 s38, s36, 0x100
	s_addc_u32 s39, s37, 0
	s_cmp_eq_u32 s59, 28
	s_cselect_b32 s43, s19, s39
	s_cselect_b32 s42, s55, s38
	s_cselect_b32 s41, s17, s58
	s_cselect_b32 s40, s56, s57
	v_lshl_add_u64 v[182:183], s[36:37], 0, v[136:137]
	s_add_i32 m0, s35, 0xc000
	s_nop 0
	global_load_lds_dwordx4 v[182:183], off
	v_lshl_add_u64 v[182:183], s[36:37], 0, v[138:139]
	s_add_i32 m0, s35, 0xe000
	s_nop 0
	global_load_lds_dwordx4 v[182:183], off
	ds_read_b128 v[182:185], v149
	ds_read_b128 v[186:189], v149 offset:1024
	ds_read_b128 v[190:193], v149 offset:2048
	ds_read_b128 v[194:197], v149 offset:3072
	ds_read_b128 v[198:201], v149 offset:4096
	ds_read_b128 v[202:205], v149 offset:5120
	ds_read_b128 v[206:209], v149 offset:6144
	ds_read_b128 v[210:213], v149 offset:7168
	s_waitcnt vmcnt(8)
	s_waitcnt lgkmcnt(0)
	s_barrier
	s_setprio 0
	s_waitcnt lgkmcnt(0)
	v_mfma_f32_16x16x32_bf16 v[124:127], v[150:153], v[182:185], v[124:127]
	v_mfma_f32_16x16x32_bf16 v[120:123], v[158:161], v[182:185], v[120:123]
	v_mfma_f32_16x16x32_bf16 v[108:111], v[150:153], v[190:193], v[108:111]
	v_mfma_f32_16x16x32_bf16 v[104:107], v[158:161], v[190:193], v[104:107]
	v_mfma_f32_16x16x32_bf16 v[92:95], v[150:153], v[198:201], v[92:95]
	v_mfma_f32_16x16x32_bf16 v[88:91], v[158:161], v[198:201], v[88:91]
	v_mfma_f32_16x16x32_bf16 v[76:79], v[150:153], v[206:209], v[76:79]
	v_mfma_f32_16x16x32_bf16 v[72:75], v[158:161], v[206:209], v[72:75]
	v_mfma_f32_16x16x32_bf16 v[124:127], v[154:157], v[186:189], v[124:127]
	v_mfma_f32_16x16x32_bf16 v[120:123], v[162:165], v[186:189], v[120:123]
	v_mfma_f32_16x16x32_bf16 v[108:111], v[154:157], v[194:197], v[108:111]
	v_mfma_f32_16x16x32_bf16 v[104:107], v[162:165], v[194:197], v[104:107]
	v_mfma_f32_16x16x32_bf16 v[92:95], v[154:157], v[202:205], v[92:95]
	v_mfma_f32_16x16x32_bf16 v[88:91], v[162:165], v[202:205], v[88:91]
	v_mfma_f32_16x16x32_bf16 v[76:79], v[154:157], v[210:213], v[76:79]
	v_mfma_f32_16x16x32_bf16 v[72:75], v[162:165], v[210:213], v[72:75]
	v_mfma_f32_16x16x32_bf16 v[116:119], v[166:169], v[182:185], v[116:119]
	v_mfma_f32_16x16x32_bf16 v[112:115], v[174:177], v[182:185], v[112:115]
	v_mfma_f32_16x16x32_bf16 v[100:103], v[166:169], v[190:193], v[100:103]
	v_mfma_f32_16x16x32_bf16 v[96:99], v[174:177], v[190:193], v[96:99]
	v_mfma_f32_16x16x32_bf16 v[84:87], v[166:169], v[198:201], v[84:87]
	v_mfma_f32_16x16x32_bf16 v[80:83], v[174:177], v[198:201], v[80:83]
	v_mfma_f32_16x16x32_bf16 v[68:71], v[166:169], v[206:209], v[68:71]
	v_mfma_f32_16x16x32_bf16 v[64:67], v[174:177], v[206:209], v[64:67]
	v_mfma_f32_16x16x32_bf16 v[116:119], v[170:173], v[186:189], v[116:119]
	v_mfma_f32_16x16x32_bf16 v[112:115], v[178:181], v[186:189], v[112:115]
	v_mfma_f32_16x16x32_bf16 v[100:103], v[170:173], v[194:197], v[100:103]
	v_mfma_f32_16x16x32_bf16 v[96:99], v[178:181], v[194:197], v[96:99]
	v_mfma_f32_16x16x32_bf16 v[84:87], v[170:173], v[202:205], v[84:87]
	v_mfma_f32_16x16x32_bf16 v[80:83], v[178:181], v[202:205], v[80:83]
	v_mfma_f32_16x16x32_bf16 v[68:71], v[170:173], v[210:213], v[68:71]
	v_mfma_f32_16x16x32_bf16 v[64:67], v[178:181], v[210:213], v[64:67]
	s_setprio 1
	s_barrier
	s_add_i32 s36, s51, s11
	v_lshl_add_u64 v[214:215], s[40:41], 0, v[130:131]
	s_mov_b32 m0, s36
	v_lshl_add_u64 v[216:217], s[40:41], 0, v[134:135]
	global_load_lds_dwordx4 v[214:215], off
	s_add_i32 m0, s36, 0x2000
	s_add_u32 s36, s40, 0x80000
	s_addc_u32 s37, s41, 0
	s_add_i32 s60, s52, s11
	global_load_lds_dwordx4 v[216:217], off
	v_lshl_add_u64 v[182:183], s[36:37], 0, v[130:131]
	s_mov_b32 m0, s60
	v_lshl_add_u64 v[218:219], s[42:43], 0, v[128:129]
	global_load_lds_dwordx4 v[182:183], off
	v_lshl_add_u64 v[182:183], s[36:37], 0, v[134:135]
	s_add_i32 m0, s60, 0x2000
	v_lshl_add_u64 v[220:221], s[42:43], 0, v[132:133]
	global_load_lds_dwordx4 v[182:183], off
	s_mov_b32 m0, s35
	s_nop 0
	global_load_lds_dwordx4 v[218:219], off
	s_mov_b32 m0, s44
	s_nop 0
	global_load_lds_dwordx4 v[220:221], off
	ds_read_b128 v[182:185], v149 offset:16384
	ds_read_b128 v[186:189], v149 offset:17408
	ds_read_b128 v[190:193], v149 offset:18432
	ds_read_b128 v[194:197], v149 offset:19456
	ds_read_b128 v[198:201], v149 offset:20480
	ds_read_b128 v[202:205], v149 offset:21504
	ds_read_b128 v[206:209], v149 offset:22528
	ds_read_b128 v[210:213], v149 offset:23552
	s_waitcnt vmcnt(8)
	s_waitcnt lgkmcnt(0)
	s_barrier
	s_setprio 0
	s_waitcnt lgkmcnt(0)
	v_mfma_f32_16x16x32_bf16 v[60:63], v[150:153], v[182:185], v[60:63]
	v_mfma_f32_16x16x32_bf16 v[56:59], v[158:161], v[182:185], v[56:59]
	v_mfma_f32_16x16x32_bf16 v[44:47], v[150:153], v[190:193], v[44:47]
	v_mfma_f32_16x16x32_bf16 v[40:43], v[158:161], v[190:193], v[40:43]
	v_mfma_f32_16x16x32_bf16 v[28:31], v[150:153], v[198:201], v[28:31]
	v_mfma_f32_16x16x32_bf16 v[24:27], v[158:161], v[198:201], v[24:27]
	v_mfma_f32_16x16x32_bf16 v[12:15], v[150:153], v[206:209], v[12:15]
	v_mfma_f32_16x16x32_bf16 v[8:11], v[158:161], v[206:209], v[8:11]
	v_mfma_f32_16x16x32_bf16 v[60:63], v[154:157], v[186:189], v[60:63]
	v_mfma_f32_16x16x32_bf16 v[56:59], v[162:165], v[186:189], v[56:59]
	v_mfma_f32_16x16x32_bf16 v[44:47], v[154:157], v[194:197], v[44:47]
	v_mfma_f32_16x16x32_bf16 v[40:43], v[162:165], v[194:197], v[40:43]
	v_mfma_f32_16x16x32_bf16 v[28:31], v[154:157], v[202:205], v[28:31]
	v_mfma_f32_16x16x32_bf16 v[24:27], v[162:165], v[202:205], v[24:27]
	v_mfma_f32_16x16x32_bf16 v[12:15], v[154:157], v[210:213], v[12:15]
	v_mfma_f32_16x16x32_bf16 v[8:11], v[162:165], v[210:213], v[8:11]
	v_mfma_f32_16x16x32_bf16 v[52:55], v[166:169], v[182:185], v[52:55]
	v_mfma_f32_16x16x32_bf16 v[48:51], v[174:177], v[182:185], v[48:51]
	v_mfma_f32_16x16x32_bf16 v[36:39], v[166:169], v[190:193], v[36:39]
	v_mfma_f32_16x16x32_bf16 v[32:35], v[174:177], v[190:193], v[32:35]
	v_mfma_f32_16x16x32_bf16 v[20:23], v[166:169], v[198:201], v[20:23]
	v_mfma_f32_16x16x32_bf16 v[16:19], v[174:177], v[198:201], v[16:19]
	v_mfma_f32_16x16x32_bf16 v[4:7], v[166:169], v[206:209], v[4:7]
	v_mfma_f32_16x16x32_bf16 v[0:3], v[174:177], v[206:209], v[0:3]
	v_mfma_f32_16x16x32_bf16 v[52:55], v[170:173], v[186:189], v[52:55]
	v_mfma_f32_16x16x32_bf16 v[48:51], v[178:181], v[186:189], v[48:51]
	v_mfma_f32_16x16x32_bf16 v[36:39], v[170:173], v[194:197], v[36:39]
	v_mfma_f32_16x16x32_bf16 v[32:35], v[178:181], v[194:197], v[32:35]
	v_mfma_f32_16x16x32_bf16 v[20:23], v[170:173], v[202:205], v[20:23]
	v_mfma_f32_16x16x32_bf16 v[16:19], v[178:181], v[202:205], v[16:19]
	v_mfma_f32_16x16x32_bf16 v[4:7], v[170:173], v[210:213], v[4:7]
	v_mfma_f32_16x16x32_bf16 v[0:3], v[178:181], v[210:213], v[0:3]
	s_setprio 1
	s_barrier
	s_add_i32 s60, 0, 0x18000
	s_add_i32 s61, 0, 0x1c000
	v_add_u32_e32 v162, s60, v144
	v_add_u32_e32 v178, s61, v144
	ds_read_b128 v[150:153], v162
	ds_read_b128 v[154:157], v162 offset:1024
	ds_read_b128 v[158:161], v162 offset:2048
	ds_read_b128 v[162:165], v162 offset:3072
	ds_read_b128 v[166:169], v178
	ds_read_b128 v[170:173], v178 offset:1024
	ds_read_b128 v[174:177], v178 offset:2048
	ds_read_b128 v[178:181], v178 offset:3072
	s_add_u32 s36, s42, 0x80000
	s_addc_u32 s37, s43, 0
	s_mov_b32 m0, s45
	v_lshl_add_u64 v[182:183], s[36:37], 0, v[128:129]
	global_load_lds_dwordx4 v[182:183], off
	v_lshl_add_u64 v[182:183], s[36:37], 0, v[132:133]
	s_mov_b32 m0, s46
	s_nop 0
	global_load_lds_dwordx4 v[182:183], off
	ds_read_b128 v[182:185], v149 offset:32768
	ds_read_b128 v[186:189], v149 offset:33792
	ds_read_b128 v[190:193], v149 offset:34816
	ds_read_b128 v[194:197], v149 offset:35840
	ds_read_b128 v[198:201], v149 offset:36864
	ds_read_b128 v[202:205], v149 offset:37888
	ds_read_b128 v[206:209], v149 offset:38912
	ds_read_b128 v[210:213], v149 offset:39936
	s_waitcnt vmcnt(8)
	s_waitcnt lgkmcnt(0)
	s_barrier
	s_setprio 0
	s_waitcnt lgkmcnt(0)
	v_mfma_f32_16x16x32_bf16 v[124:127], v[150:153], v[182:185], v[124:127]
	v_mfma_f32_16x16x32_bf16 v[120:123], v[158:161], v[182:185], v[120:123]
	v_mfma_f32_16x16x32_bf16 v[108:111], v[150:153], v[190:193], v[108:111]
	v_mfma_f32_16x16x32_bf16 v[104:107], v[158:161], v[190:193], v[104:107]
	v_mfma_f32_16x16x32_bf16 v[92:95], v[150:153], v[198:201], v[92:95]
	v_mfma_f32_16x16x32_bf16 v[88:91], v[158:161], v[198:201], v[88:91]
	v_mfma_f32_16x16x32_bf16 v[76:79], v[150:153], v[206:209], v[76:79]
	v_mfma_f32_16x16x32_bf16 v[72:75], v[158:161], v[206:209], v[72:75]
	v_mfma_f32_16x16x32_bf16 v[124:127], v[154:157], v[186:189], v[124:127]
	v_mfma_f32_16x16x32_bf16 v[120:123], v[162:165], v[186:189], v[120:123]
	v_mfma_f32_16x16x32_bf16 v[108:111], v[154:157], v[194:197], v[108:111]
	v_mfma_f32_16x16x32_bf16 v[104:107], v[162:165], v[194:197], v[104:107]
	v_mfma_f32_16x16x32_bf16 v[92:95], v[154:157], v[202:205], v[92:95]
	v_mfma_f32_16x16x32_bf16 v[88:91], v[162:165], v[202:205], v[88:91]
	v_mfma_f32_16x16x32_bf16 v[76:79], v[154:157], v[210:213], v[76:79]
	v_mfma_f32_16x16x32_bf16 v[72:75], v[162:165], v[210:213], v[72:75]
	v_mfma_f32_16x16x32_bf16 v[116:119], v[166:169], v[182:185], v[116:119]
	v_mfma_f32_16x16x32_bf16 v[112:115], v[174:177], v[182:185], v[112:115]
	v_mfma_f32_16x16x32_bf16 v[100:103], v[166:169], v[190:193], v[100:103]
	v_mfma_f32_16x16x32_bf16 v[96:99], v[174:177], v[190:193], v[96:99]
	v_mfma_f32_16x16x32_bf16 v[84:87], v[166:169], v[198:201], v[84:87]
	v_mfma_f32_16x16x32_bf16 v[80:83], v[174:177], v[198:201], v[80:83]
	v_mfma_f32_16x16x32_bf16 v[68:71], v[166:169], v[206:209], v[68:71]
	v_mfma_f32_16x16x32_bf16 v[64:67], v[174:177], v[206:209], v[64:67]
	v_mfma_f32_16x16x32_bf16 v[116:119], v[170:173], v[186:189], v[116:119]
	v_mfma_f32_16x16x32_bf16 v[112:115], v[178:181], v[186:189], v[112:115]
	v_mfma_f32_16x16x32_bf16 v[100:103], v[170:173], v[194:197], v[100:103]
	v_mfma_f32_16x16x32_bf16 v[96:99], v[178:181], v[194:197], v[96:99]
	v_mfma_f32_16x16x32_bf16 v[84:87], v[170:173], v[202:205], v[84:87]
	v_mfma_f32_16x16x32_bf16 v[80:83], v[178:181], v[202:205], v[80:83]
	v_mfma_f32_16x16x32_bf16 v[68:71], v[170:173], v[210:213], v[68:71]
	v_mfma_f32_16x16x32_bf16 v[64:67], v[178:181], v[210:213], v[64:67]
	s_setprio 1
	s_barrier
	s_add_i32 s36, s60, s11
	v_lshl_add_u64 v[182:183], v[214:215], 0, s[14:15]
	s_mov_b32 m0, s36
	s_nop 0
	global_load_lds_dwordx4 v[182:183], off
	s_add_i32 m0, s36, 0x2000
	s_add_u32 s36, s40, 0x80080
	v_lshl_add_u64 v[182:183], v[216:217], 0, s[14:15]
	s_addc_u32 s37, s41, 0
	s_add_i32 s40, s61, s11
	global_load_lds_dwordx4 v[182:183], off
	v_lshl_add_u64 v[182:183], s[36:37], 0, v[130:131]
	s_mov_b32 m0, s40
	s_nop 0
	global_load_lds_dwordx4 v[182:183], off
	v_lshl_add_u64 v[182:183], s[36:37], 0, v[134:135]
	s_add_i32 m0, s40, 0x2000
	s_nop 0
	global_load_lds_dwordx4 v[182:183], off
	v_lshl_add_u64 v[182:183], v[218:219], 0, s[14:15]
	s_mov_b32 m0, s49
	s_nop 0
	global_load_lds_dwordx4 v[182:183], off
	v_lshl_add_u64 v[182:183], v[220:221], 0, s[14:15]
	s_mov_b32 m0, s50
	s_nop 0
	global_load_lds_dwordx4 v[182:183], off
	ds_read_b128 v[182:185], v149 offset:49152
	ds_read_b128 v[186:189], v149 offset:50176
	ds_read_b128 v[190:193], v149 offset:51200
	ds_read_b128 v[194:197], v149 offset:52224
	ds_read_b128 v[198:201], v149 offset:53248
	ds_read_b128 v[202:205], v149 offset:54272
	ds_read_b128 v[206:209], v149 offset:55296
	ds_read_b128 v[210:213], v149 offset:56320
	s_waitcnt vmcnt(8)
	s_waitcnt lgkmcnt(0)
	s_barrier
	s_setprio 0
	s_waitcnt lgkmcnt(0)
	v_mfma_f32_16x16x32_bf16 v[60:63], v[150:153], v[182:185], v[60:63]
	v_mfma_f32_16x16x32_bf16 v[56:59], v[158:161], v[182:185], v[56:59]
	v_mfma_f32_16x16x32_bf16 v[44:47], v[150:153], v[190:193], v[44:47]
	v_mfma_f32_16x16x32_bf16 v[40:43], v[158:161], v[190:193], v[40:43]
	v_mfma_f32_16x16x32_bf16 v[28:31], v[150:153], v[198:201], v[28:31]
	v_mfma_f32_16x16x32_bf16 v[24:27], v[158:161], v[198:201], v[24:27]
	v_mfma_f32_16x16x32_bf16 v[12:15], v[150:153], v[206:209], v[12:15]
	v_mfma_f32_16x16x32_bf16 v[8:11], v[158:161], v[206:209], v[8:11]
	v_mfma_f32_16x16x32_bf16 v[60:63], v[154:157], v[186:189], v[60:63]
	v_mfma_f32_16x16x32_bf16 v[56:59], v[162:165], v[186:189], v[56:59]
	v_mfma_f32_16x16x32_bf16 v[44:47], v[154:157], v[194:197], v[44:47]
	v_mfma_f32_16x16x32_bf16 v[40:43], v[162:165], v[194:197], v[40:43]
	v_mfma_f32_16x16x32_bf16 v[28:31], v[154:157], v[202:205], v[28:31]
	v_mfma_f32_16x16x32_bf16 v[24:27], v[162:165], v[202:205], v[24:27]
	v_mfma_f32_16x16x32_bf16 v[12:15], v[154:157], v[210:213], v[12:15]
	v_mfma_f32_16x16x32_bf16 v[8:11], v[162:165], v[210:213], v[8:11]
	v_mfma_f32_16x16x32_bf16 v[52:55], v[166:169], v[182:185], v[52:55]
	v_mfma_f32_16x16x32_bf16 v[48:51], v[174:177], v[182:185], v[48:51]
	v_mfma_f32_16x16x32_bf16 v[36:39], v[166:169], v[190:193], v[36:39]
	v_mfma_f32_16x16x32_bf16 v[32:35], v[174:177], v[190:193], v[32:35]
	v_mfma_f32_16x16x32_bf16 v[20:23], v[166:169], v[198:201], v[20:23]
	v_mfma_f32_16x16x32_bf16 v[16:19], v[174:177], v[198:201], v[16:19]
	v_mfma_f32_16x16x32_bf16 v[4:7], v[166:169], v[206:209], v[4:7]
	v_mfma_f32_16x16x32_bf16 v[0:3], v[174:177], v[206:209], v[0:3]
	v_mfma_f32_16x16x32_bf16 v[52:55], v[170:173], v[186:189], v[52:55]
	v_mfma_f32_16x16x32_bf16 v[48:51], v[178:181], v[186:189], v[48:51]
	v_mfma_f32_16x16x32_bf16 v[36:39], v[170:173], v[194:197], v[36:39]
	v_mfma_f32_16x16x32_bf16 v[32:35], v[178:181], v[194:197], v[32:35]
	v_mfma_f32_16x16x32_bf16 v[20:23], v[170:173], v[202:205], v[20:23]
	v_mfma_f32_16x16x32_bf16 v[16:19], v[178:181], v[202:205], v[16:19]
	v_mfma_f32_16x16x32_bf16 v[4:7], v[170:173], v[210:213], v[4:7]
	v_mfma_f32_16x16x32_bf16 v[0:3], v[178:181], v[210:213], v[0:3]
	s_setprio 1
	s_barrier
	s_add_i32 s59, s59, 2
	s_add_u32 s57, s57, 0x100
	s_addc_u32 s58, s58, 0
	s_cmp_gt_u32 s59, 29
	s_mov_b64 s[36:37], s[38:39]
	s_cbranch_scc0 .LBB0_159
	s_setprio 0
	s_and_b64 vcc, exec, s[6:7]
	s_cbranch_vccz .LBB0_162
	s_barrier

.LBB0_248:
	ds_read_b128 v[144:147], v161
	ds_read_b128 v[148:151], v161 offset:1024
	ds_read_b128 v[152:155], v161 offset:2048
	ds_read_b128 v[164:167], v161 offset:3072
	ds_read_b128 v[168:171], v162
	ds_read_b128 v[172:175], v162 offset:1024
	ds_read_b128 v[176:179], v162 offset:2048
	ds_read_b128 v[180:183], v162 offset:3072
	s_add_u32 s6, s8, 0x100
	s_addc_u32 s7, s9, 0
	s_cmpk_eq_i32 s65, 0x54
	s_cselect_b32 s49, s43, s7
	s_cselect_b32 s48, s42, s6
	s_cselect_b32 s47, s45, s64
	s_cselect_b32 s46, s44, s63
	v_lshl_add_u64 v[184:185], s[8:9], 0, v[136:137]
	s_add_i32 m0, s53, 0xc000
	s_nop 0
	global_load_lds_dwordx4 v[184:185], off
	v_lshl_add_u64 v[184:185], s[8:9], 0, v[138:139]
	s_add_i32 m0, s53, 0xe000
	s_nop 0
	global_load_lds_dwordx4 v[184:185], off
	ds_read_b128 v[184:187], v163
	ds_read_b128 v[188:191], v163 offset:1024
	ds_read_b128 v[192:195], v163 offset:2048
	ds_read_b128 v[196:199], v163 offset:3072
	ds_read_b128 v[200:203], v163 offset:4096
	ds_read_b128 v[204:207], v163 offset:5120
	ds_read_b128 v[208:211], v163 offset:6144
	ds_read_b128 v[212:215], v163 offset:7168
	s_waitcnt vmcnt(8)
	s_waitcnt lgkmcnt(0)
	s_barrier
	s_setprio 0
	s_waitcnt lgkmcnt(0)
	v_mfma_f32_16x16x32_bf16 v[124:127], v[144:147], v[184:187], v[124:127]
	v_mfma_f32_16x16x32_bf16 v[120:123], v[152:155], v[184:187], v[120:123]
	v_mfma_f32_16x16x32_bf16 v[108:111], v[144:147], v[192:195], v[108:111]
	v_mfma_f32_16x16x32_bf16 v[104:107], v[152:155], v[192:195], v[104:107]
	v_mfma_f32_16x16x32_bf16 v[92:95], v[144:147], v[200:203], v[92:95]
	v_mfma_f32_16x16x32_bf16 v[88:91], v[152:155], v[200:203], v[88:91]
	v_mfma_f32_16x16x32_bf16 v[76:79], v[144:147], v[208:211], v[76:79]
	v_mfma_f32_16x16x32_bf16 v[72:75], v[152:155], v[208:211], v[72:75]
	v_mfma_f32_16x16x32_bf16 v[124:127], v[148:151], v[188:191], v[124:127]
	v_mfma_f32_16x16x32_bf16 v[120:123], v[164:167], v[188:191], v[120:123]
	v_mfma_f32_16x16x32_bf16 v[108:111], v[148:151], v[196:199], v[108:111]
	v_mfma_f32_16x16x32_bf16 v[104:107], v[164:167], v[196:199], v[104:107]
	v_mfma_f32_16x16x32_bf16 v[92:95], v[148:151], v[204:207], v[92:95]
	v_mfma_f32_16x16x32_bf16 v[88:91], v[164:167], v[204:207], v[88:91]
	v_mfma_f32_16x16x32_bf16 v[76:79], v[148:151], v[212:215], v[76:79]
	v_mfma_f32_16x16x32_bf16 v[72:75], v[164:167], v[212:215], v[72:75]
	v_mfma_f32_16x16x32_bf16 v[116:119], v[168:171], v[184:187], v[116:119]
	v_mfma_f32_16x16x32_bf16 v[112:115], v[176:179], v[184:187], v[112:115]
	v_mfma_f32_16x16x32_bf16 v[100:103], v[168:171], v[192:195], v[100:103]
	v_mfma_f32_16x16x32_bf16 v[96:99], v[176:179], v[192:195], v[96:99]
	v_mfma_f32_16x16x32_bf16 v[84:87], v[168:171], v[200:203], v[84:87]
	v_mfma_f32_16x16x32_bf16 v[80:83], v[176:179], v[200:203], v[80:83]
	v_mfma_f32_16x16x32_bf16 v[68:71], v[168:171], v[208:211], v[68:71]
	v_mfma_f32_16x16x32_bf16 v[64:67], v[176:179], v[208:211], v[64:67]
	v_mfma_f32_16x16x32_bf16 v[116:119], v[172:175], v[188:191], v[116:119]
	v_mfma_f32_16x16x32_bf16 v[112:115], v[180:183], v[188:191], v[112:115]
	v_mfma_f32_16x16x32_bf16 v[100:103], v[172:175], v[196:199], v[100:103]
	v_mfma_f32_16x16x32_bf16 v[96:99], v[180:183], v[196:199], v[96:99]
	v_mfma_f32_16x16x32_bf16 v[84:87], v[172:175], v[204:207], v[84:87]
	v_mfma_f32_16x16x32_bf16 v[80:83], v[180:183], v[204:207], v[80:83]
	v_mfma_f32_16x16x32_bf16 v[68:71], v[172:175], v[212:215], v[68:71]
	v_mfma_f32_16x16x32_bf16 v[64:67], v[180:183], v[212:215], v[64:67]
	s_setprio 1
	s_barrier
	s_add_i32 s8, s58, s21
	v_lshl_add_u64 v[216:217], s[46:47], 0, v[130:131]
	s_mov_b32 m0, s8
	v_lshl_add_u64 v[218:219], s[46:47], 0, v[134:135]
	global_load_lds_dwordx4 v[216:217], off
	s_add_i32 m0, s8, 0x2000
	s_add_u32 s8, s46, 0x160000
	s_addc_u32 s9, s47, 0
	s_add_i32 s66, s59, s21
	global_load_lds_dwordx4 v[218:219], off
	v_lshl_add_u64 v[184:185], s[8:9], 0, v[130:131]
	s_mov_b32 m0, s66
	v_lshl_add_u64 v[220:221], s[48:49], 0, v[128:129]
	global_load_lds_dwordx4 v[184:185], off
	v_lshl_add_u64 v[184:185], s[8:9], 0, v[134:135]
	s_add_i32 m0, s66, 0x2000
	v_lshl_add_u64 v[222:223], s[48:49], 0, v[132:133]
	global_load_lds_dwordx4 v[184:185], off
	s_mov_b32 m0, s53
	s_nop 0
	global_load_lds_dwordx4 v[220:221], off
	s_mov_b32 m0, s54
	s_nop 0
	global_load_lds_dwordx4 v[222:223], off
	ds_read_b128 v[184:187], v163 offset:16384
	ds_read_b128 v[188:191], v163 offset:17408
	ds_read_b128 v[192:195], v163 offset:18432
	ds_read_b128 v[196:199], v163 offset:19456
	ds_read_b128 v[200:203], v163 offset:20480
	ds_read_b128 v[204:207], v163 offset:21504
	ds_read_b128 v[208:211], v163 offset:22528
	ds_read_b128 v[212:215], v163 offset:23552
	s_waitcnt vmcnt(8)
	s_waitcnt lgkmcnt(0)
	s_barrier
	s_setprio 0
	s_waitcnt lgkmcnt(0)
	v_mfma_f32_16x16x32_bf16 v[60:63], v[144:147], v[184:187], v[60:63]
	v_mfma_f32_16x16x32_bf16 v[56:59], v[152:155], v[184:187], v[56:59]
	v_mfma_f32_16x16x32_bf16 v[44:47], v[144:147], v[192:195], v[44:47]
	v_mfma_f32_16x16x32_bf16 v[40:43], v[152:155], v[192:195], v[40:43]
	v_mfma_f32_16x16x32_bf16 v[28:31], v[144:147], v[200:203], v[28:31]
	v_mfma_f32_16x16x32_bf16 v[24:27], v[152:155], v[200:203], v[24:27]
	v_mfma_f32_16x16x32_bf16 v[12:15], v[144:147], v[208:211], v[12:15]
	v_mfma_f32_16x16x32_bf16 v[8:11], v[152:155], v[208:211], v[8:11]
	v_mfma_f32_16x16x32_bf16 v[60:63], v[148:151], v[188:191], v[60:63]
	v_mfma_f32_16x16x32_bf16 v[56:59], v[164:167], v[188:191], v[56:59]
	v_mfma_f32_16x16x32_bf16 v[44:47], v[148:151], v[196:199], v[44:47]
	v_mfma_f32_16x16x32_bf16 v[40:43], v[164:167], v[196:199], v[40:43]
	v_mfma_f32_16x16x32_bf16 v[28:31], v[148:151], v[204:207], v[28:31]
	v_mfma_f32_16x16x32_bf16 v[24:27], v[164:167], v[204:207], v[24:27]
	v_mfma_f32_16x16x32_bf16 v[12:15], v[148:151], v[212:215], v[12:15]
	v_mfma_f32_16x16x32_bf16 v[8:11], v[164:167], v[212:215], v[8:11]
	v_mfma_f32_16x16x32_bf16 v[52:55], v[168:171], v[184:187], v[52:55]
	v_mfma_f32_16x16x32_bf16 v[48:51], v[176:179], v[184:187], v[48:51]
	v_mfma_f32_16x16x32_bf16 v[36:39], v[168:171], v[192:195], v[36:39]
	v_mfma_f32_16x16x32_bf16 v[32:35], v[176:179], v[192:195], v[32:35]
	v_mfma_f32_16x16x32_bf16 v[20:23], v[168:171], v[200:203], v[20:23]
	v_mfma_f32_16x16x32_bf16 v[16:19], v[176:179], v[200:203], v[16:19]
	v_mfma_f32_16x16x32_bf16 v[4:7], v[168:171], v[208:211], v[4:7]
	v_mfma_f32_16x16x32_bf16 v[0:3], v[176:179], v[208:211], v[0:3]
	v_mfma_f32_16x16x32_bf16 v[52:55], v[172:175], v[188:191], v[52:55]
	v_mfma_f32_16x16x32_bf16 v[48:51], v[180:183], v[188:191], v[48:51]
	v_mfma_f32_16x16x32_bf16 v[36:39], v[172:175], v[196:199], v[36:39]
	v_mfma_f32_16x16x32_bf16 v[32:35], v[180:183], v[196:199], v[32:35]
	v_mfma_f32_16x16x32_bf16 v[20:23], v[172:175], v[204:207], v[20:23]
	v_mfma_f32_16x16x32_bf16 v[16:19], v[180:183], v[204:207], v[16:19]
	v_mfma_f32_16x16x32_bf16 v[4:7], v[172:175], v[212:215], v[4:7]
	v_mfma_f32_16x16x32_bf16 v[0:3], v[180:183], v[212:215], v[0:3]
	s_setprio 1
	s_barrier
	s_add_i32 s66, 0, 0x18000
	s_add_i32 s67, 0, 0x1c000
	v_add_u32_e32 v164, s66, v156
	v_add_u32_e32 v180, s67, v156
	ds_read_b128 v[144:147], v164
	ds_read_b128 v[148:151], v164 offset:1024
	ds_read_b128 v[152:155], v164 offset:2048
	ds_read_b128 v[164:167], v164 offset:3072
	ds_read_b128 v[168:171], v180
	ds_read_b128 v[172:175], v180 offset:1024
	ds_read_b128 v[176:179], v180 offset:2048
	ds_read_b128 v[180:183], v180 offset:3072
	s_add_u32 s8, s48, 0x160000
	s_addc_u32 s9, s49, 0
	s_mov_b32 m0, s55
	v_lshl_add_u64 v[184:185], s[8:9], 0, v[128:129]
	global_load_lds_dwordx4 v[184:185], off
	v_lshl_add_u64 v[184:185], s[8:9], 0, v[132:133]
	s_mov_b32 m0, s56
	s_nop 0
	global_load_lds_dwordx4 v[184:185], off
	ds_read_b128 v[184:187], v163 offset:32768
	ds_read_b128 v[188:191], v163 offset:33792
	ds_read_b128 v[192:195], v163 offset:34816
	ds_read_b128 v[196:199], v163 offset:35840
	ds_read_b128 v[200:203], v163 offset:36864
	ds_read_b128 v[204:207], v163 offset:37888
	ds_read_b128 v[208:211], v163 offset:38912
	ds_read_b128 v[212:215], v163 offset:39936
	s_waitcnt vmcnt(8)
	s_waitcnt lgkmcnt(0)
	s_barrier
	s_setprio 0
	s_waitcnt lgkmcnt(0)
	v_mfma_f32_16x16x32_bf16 v[124:127], v[144:147], v[184:187], v[124:127]
	v_mfma_f32_16x16x32_bf16 v[120:123], v[152:155], v[184:187], v[120:123]
	v_mfma_f32_16x16x32_bf16 v[108:111], v[144:147], v[192:195], v[108:111]
	v_mfma_f32_16x16x32_bf16 v[104:107], v[152:155], v[192:195], v[104:107]
	v_mfma_f32_16x16x32_bf16 v[92:95], v[144:147], v[200:203], v[92:95]
	v_mfma_f32_16x16x32_bf16 v[88:91], v[152:155], v[200:203], v[88:91]
	v_mfma_f32_16x16x32_bf16 v[76:79], v[144:147], v[208:211], v[76:79]
	v_mfma_f32_16x16x32_bf16 v[72:75], v[152:155], v[208:211], v[72:75]
	v_mfma_f32_16x16x32_bf16 v[124:127], v[148:151], v[188:191], v[124:127]
	v_mfma_f32_16x16x32_bf16 v[120:123], v[164:167], v[188:191], v[120:123]
	v_mfma_f32_16x16x32_bf16 v[108:111], v[148:151], v[196:199], v[108:111]
	v_mfma_f32_16x16x32_bf16 v[104:107], v[164:167], v[196:199], v[104:107]
	v_mfma_f32_16x16x32_bf16 v[92:95], v[148:151], v[204:207], v[92:95]
	v_mfma_f32_16x16x32_bf16 v[88:91], v[164:167], v[204:207], v[88:91]
	v_mfma_f32_16x16x32_bf16 v[76:79], v[148:151], v[212:215], v[76:79]
	v_mfma_f32_16x16x32_bf16 v[72:75], v[164:167], v[212:215], v[72:75]
	v_mfma_f32_16x16x32_bf16 v[116:119], v[168:171], v[184:187], v[116:119]
	v_mfma_f32_16x16x32_bf16 v[112:115], v[176:179], v[184:187], v[112:115]
	v_mfma_f32_16x16x32_bf16 v[100:103], v[168:171], v[192:195], v[100:103]
	v_mfma_f32_16x16x32_bf16 v[96:99], v[176:179], v[192:195], v[96:99]
	v_mfma_f32_16x16x32_bf16 v[84:87], v[168:171], v[200:203], v[84:87]
	v_mfma_f32_16x16x32_bf16 v[80:83], v[176:179], v[200:203], v[80:83]
	v_mfma_f32_16x16x32_bf16 v[68:71], v[168:171], v[208:211], v[68:71]
	v_mfma_f32_16x16x32_bf16 v[64:67], v[176:179], v[208:211], v[64:67]
	v_mfma_f32_16x16x32_bf16 v[116:119], v[172:175], v[188:191], v[116:119]
	v_mfma_f32_16x16x32_bf16 v[112:115], v[180:183], v[188:191], v[112:115]
	v_mfma_f32_16x16x32_bf16 v[100:103], v[172:175], v[196:199], v[100:103]
	v_mfma_f32_16x16x32_bf16 v[96:99], v[180:183], v[196:199], v[96:99]
	v_mfma_f32_16x16x32_bf16 v[84:87], v[172:175], v[204:207], v[84:87]
	v_mfma_f32_16x16x32_bf16 v[80:83], v[180:183], v[204:207], v[80:83]
	v_mfma_f32_16x16x32_bf16 v[68:71], v[172:175], v[212:215], v[68:71]
	v_mfma_f32_16x16x32_bf16 v[64:67], v[180:183], v[212:215], v[64:67]
	s_setprio 1
	s_barrier
	s_add_i32 s8, s66, s21
	v_lshl_add_u64 v[184:185], v[216:217], 0, s[36:37]
	s_mov_b32 m0, s8
	s_nop 0
	global_load_lds_dwordx4 v[184:185], off
	s_add_i32 m0, s8, 0x2000
	s_add_u32 s8, s46, 0x160080
	v_lshl_add_u64 v[184:185], v[218:219], 0, s[36:37]
	s_addc_u32 s9, s47, 0
	s_add_i32 s46, s67, s21
	global_load_lds_dwordx4 v[184:185], off
	v_lshl_add_u64 v[184:185], s[8:9], 0, v[130:131]
	s_mov_b32 m0, s46
	s_nop 0
	global_load_lds_dwordx4 v[184:185], off
	v_lshl_add_u64 v[184:185], s[8:9], 0, v[134:135]
	s_add_i32 m0, s46, 0x2000
	s_nop 0
	global_load_lds_dwordx4 v[184:185], off
	v_lshl_add_u64 v[184:185], v[220:221], 0, s[36:37]
	s_mov_b32 m0, s26
	s_nop 0
	global_load_lds_dwordx4 v[184:185], off
	v_lshl_add_u64 v[184:185], v[222:223], 0, s[36:37]
	s_mov_b32 m0, s27
	s_nop 0
	global_load_lds_dwordx4 v[184:185], off
	ds_read_b128 v[184:187], v163 offset:49152
	ds_read_b128 v[188:191], v163 offset:50176
	ds_read_b128 v[192:195], v163 offset:51200
	ds_read_b128 v[196:199], v163 offset:52224
	ds_read_b128 v[200:203], v163 offset:53248
	ds_read_b128 v[204:207], v163 offset:54272
	ds_read_b128 v[208:211], v163 offset:55296
	ds_read_b128 v[212:215], v163 offset:56320
	s_waitcnt vmcnt(8)
	s_waitcnt lgkmcnt(0)
	s_barrier
	s_setprio 0
	s_waitcnt lgkmcnt(0)
	v_mfma_f32_16x16x32_bf16 v[60:63], v[144:147], v[184:187], v[60:63]
	v_mfma_f32_16x16x32_bf16 v[56:59], v[152:155], v[184:187], v[56:59]
	v_mfma_f32_16x16x32_bf16 v[44:47], v[144:147], v[192:195], v[44:47]
	v_mfma_f32_16x16x32_bf16 v[40:43], v[152:155], v[192:195], v[40:43]
	v_mfma_f32_16x16x32_bf16 v[28:31], v[144:147], v[200:203], v[28:31]
	v_mfma_f32_16x16x32_bf16 v[24:27], v[152:155], v[200:203], v[24:27]
	v_mfma_f32_16x16x32_bf16 v[12:15], v[144:147], v[208:211], v[12:15]
	v_mfma_f32_16x16x32_bf16 v[8:11], v[152:155], v[208:211], v[8:11]
	v_mfma_f32_16x16x32_bf16 v[60:63], v[148:151], v[188:191], v[60:63]
	v_mfma_f32_16x16x32_bf16 v[56:59], v[164:167], v[188:191], v[56:59]
	v_mfma_f32_16x16x32_bf16 v[44:47], v[148:151], v[196:199], v[44:47]
	v_mfma_f32_16x16x32_bf16 v[40:43], v[164:167], v[196:199], v[40:43]
	v_mfma_f32_16x16x32_bf16 v[28:31], v[148:151], v[204:207], v[28:31]
	v_mfma_f32_16x16x32_bf16 v[24:27], v[164:167], v[204:207], v[24:27]
	v_mfma_f32_16x16x32_bf16 v[12:15], v[148:151], v[212:215], v[12:15]
	v_mfma_f32_16x16x32_bf16 v[8:11], v[164:167], v[212:215], v[8:11]
	v_mfma_f32_16x16x32_bf16 v[52:55], v[168:171], v[184:187], v[52:55]
	v_mfma_f32_16x16x32_bf16 v[48:51], v[176:179], v[184:187], v[48:51]
	v_mfma_f32_16x16x32_bf16 v[36:39], v[168:171], v[192:195], v[36:39]
	v_mfma_f32_16x16x32_bf16 v[32:35], v[176:179], v[192:195], v[32:35]
	v_mfma_f32_16x16x32_bf16 v[20:23], v[168:171], v[200:203], v[20:23]
	v_mfma_f32_16x16x32_bf16 v[16:19], v[176:179], v[200:203], v[16:19]
	v_mfma_f32_16x16x32_bf16 v[4:7], v[168:171], v[208:211], v[4:7]
	v_mfma_f32_16x16x32_bf16 v[0:3], v[176:179], v[208:211], v[0:3]
	v_mfma_f32_16x16x32_bf16 v[52:55], v[172:175], v[188:191], v[52:55]
	v_mfma_f32_16x16x32_bf16 v[48:51], v[180:183], v[188:191], v[48:51]
	v_mfma_f32_16x16x32_bf16 v[36:39], v[172:175], v[196:199], v[36:39]
	v_mfma_f32_16x16x32_bf16 v[32:35], v[180:183], v[196:199], v[32:35]
	v_mfma_f32_16x16x32_bf16 v[20:23], v[172:175], v[204:207], v[20:23]
	v_mfma_f32_16x16x32_bf16 v[16:19], v[180:183], v[204:207], v[16:19]
	v_mfma_f32_16x16x32_bf16 v[4:7], v[172:175], v[212:215], v[4:7]
	v_mfma_f32_16x16x32_bf16 v[0:3], v[180:183], v[212:215], v[0:3]
	s_setprio 1
	s_barrier
	s_add_i32 s65, s65, 2
	s_add_u32 s63, s63, 0x100
	s_addc_u32 s64, s64, 0
	s_cmpk_gt_u32 s65, 0x55
	s_mov_b64 s[8:9], s[6:7]
	s_cbranch_scc0 .LBB0_248
	s_setprio 0
	s_and_b64 vcc, exec, s[28:29]
	s_cbranch_vccz .LBB0_251
	s_barrier

.LBB0_387:
	ds_read_b128 v[146:149], v156
	ds_read_b128 v[160:163], v156 offset:1024
	ds_read_b128 v[164:167], v156 offset:2048
	ds_read_b128 v[168:171], v156 offset:3072
	ds_read_b128 v[172:175], v157
	ds_read_b128 v[176:179], v157 offset:1024
	ds_read_b128 v[180:183], v157 offset:2048
	ds_read_b128 v[184:187], v157 offset:3072
	s_add_u32 s38, s36, 0x100
	s_addc_u32 s39, s37, 0
	s_cmp_eq_u32 s64, 28
	s_cselect_b32 s43, s29, s39
	s_cselect_b32 s42, s60, s38
	s_cselect_b32 s41, s19, s63
	s_cselect_b32 s40, s61, s62
	v_lshl_add_u64 v[150:151], s[36:37], 0, v[138:139]
	s_add_i32 m0, s46, 0xc000
	s_nop 0
	global_load_lds_dwordx4 v[150:151], off
	v_lshl_add_u64 v[150:151], s[36:37], 0, v[140:141]
	s_add_i32 m0, s46, 0xe000
	s_nop 0
	global_load_lds_dwordx4 v[150:151], off
	ds_read_b128 v[188:191], v158
	ds_read_b128 v[192:195], v158 offset:1024
	ds_read_b128 v[196:199], v158 offset:2048
	ds_read_b128 v[200:203], v158 offset:3072
	ds_read_b128 v[204:207], v158 offset:4096
	ds_read_b128 v[208:211], v158 offset:5120
	ds_read_b128 v[212:215], v158 offset:6144
	ds_read_b128 v[216:219], v158 offset:7168
	s_waitcnt vmcnt(8)
	s_waitcnt lgkmcnt(0)
	s_barrier
	s_setprio 0
	s_waitcnt lgkmcnt(0)
	v_mfma_f32_16x16x32_bf16 v[124:127], v[146:149], v[188:191], v[124:127]
	v_mfma_f32_16x16x32_bf16 v[120:123], v[164:167], v[188:191], v[120:123]
	v_mfma_f32_16x16x32_bf16 v[108:111], v[146:149], v[196:199], v[108:111]
	v_mfma_f32_16x16x32_bf16 v[104:107], v[164:167], v[196:199], v[104:107]
	v_mfma_f32_16x16x32_bf16 v[92:95], v[146:149], v[204:207], v[92:95]
	v_mfma_f32_16x16x32_bf16 v[88:91], v[164:167], v[204:207], v[88:91]
	v_mfma_f32_16x16x32_bf16 v[76:79], v[146:149], v[212:215], v[76:79]
	v_mfma_f32_16x16x32_bf16 v[72:75], v[164:167], v[212:215], v[72:75]
	v_mfma_f32_16x16x32_bf16 v[124:127], v[160:163], v[192:195], v[124:127]
	v_mfma_f32_16x16x32_bf16 v[120:123], v[168:171], v[192:195], v[120:123]
	v_mfma_f32_16x16x32_bf16 v[108:111], v[160:163], v[200:203], v[108:111]
	v_mfma_f32_16x16x32_bf16 v[104:107], v[168:171], v[200:203], v[104:107]
	v_mfma_f32_16x16x32_bf16 v[92:95], v[160:163], v[208:211], v[92:95]
	v_mfma_f32_16x16x32_bf16 v[88:91], v[168:171], v[208:211], v[88:91]
	v_mfma_f32_16x16x32_bf16 v[76:79], v[160:163], v[216:219], v[76:79]
	v_mfma_f32_16x16x32_bf16 v[72:75], v[168:171], v[216:219], v[72:75]
	v_mfma_f32_16x16x32_bf16 v[116:119], v[172:175], v[188:191], v[116:119]
	v_mfma_f32_16x16x32_bf16 v[112:115], v[180:183], v[188:191], v[112:115]
	v_mfma_f32_16x16x32_bf16 v[100:103], v[172:175], v[196:199], v[100:103]
	v_mfma_f32_16x16x32_bf16 v[96:99], v[180:183], v[196:199], v[96:99]
	v_mfma_f32_16x16x32_bf16 v[84:87], v[172:175], v[204:207], v[84:87]
	v_mfma_f32_16x16x32_bf16 v[80:83], v[180:183], v[204:207], v[80:83]
	v_mfma_f32_16x16x32_bf16 v[68:71], v[172:175], v[212:215], v[68:71]
	v_mfma_f32_16x16x32_bf16 v[64:67], v[180:183], v[212:215], v[64:67]
	v_mfma_f32_16x16x32_bf16 v[116:119], v[176:179], v[192:195], v[116:119]
	v_mfma_f32_16x16x32_bf16 v[112:115], v[184:187], v[192:195], v[112:115]
	v_mfma_f32_16x16x32_bf16 v[100:103], v[176:179], v[200:203], v[100:103]
	v_mfma_f32_16x16x32_bf16 v[96:99], v[184:187], v[200:203], v[96:99]
	v_mfma_f32_16x16x32_bf16 v[84:87], v[176:179], v[208:211], v[84:87]
	v_mfma_f32_16x16x32_bf16 v[80:83], v[184:187], v[208:211], v[80:83]
	v_mfma_f32_16x16x32_bf16 v[68:71], v[176:179], v[216:219], v[68:71]
	v_mfma_f32_16x16x32_bf16 v[64:67], v[184:187], v[216:219], v[64:67]
	s_setprio 1
	s_barrier
	s_add_i32 s36, s55, s11
	v_lshl_add_u64 v[150:151], s[40:41], 0, v[130:131]
	s_mov_b32 m0, s36
	v_lshl_add_u64 v[220:221], s[40:41], 0, v[134:135]
	global_load_lds_dwordx4 v[150:151], off
	s_add_i32 m0, s36, 0x2000
	s_add_u32 s36, s40, 0x80000
	s_addc_u32 s37, s41, 0
	s_add_i32 s65, s56, s11
	global_load_lds_dwordx4 v[220:221], off
	v_lshl_add_u64 v[188:189], s[36:37], 0, v[130:131]
	s_mov_b32 m0, s65
	v_lshl_add_u64 v[222:223], s[42:43], 0, v[128:129]
	global_load_lds_dwordx4 v[188:189], off
	v_lshl_add_u64 v[188:189], s[36:37], 0, v[134:135]
	s_add_i32 m0, s65, 0x2000
	v_lshl_add_u64 v[224:225], s[42:43], 0, v[132:133]
	global_load_lds_dwordx4 v[188:189], off
	s_mov_b32 m0, s46
	s_nop 0
	global_load_lds_dwordx4 v[222:223], off
	s_mov_b32 m0, s47
	s_nop 0
	global_load_lds_dwordx4 v[224:225], off
	ds_read_b128 v[188:191], v158 offset:16384
	ds_read_b128 v[192:195], v158 offset:17408
	ds_read_b128 v[196:199], v158 offset:18432
	ds_read_b128 v[200:203], v158 offset:19456
	ds_read_b128 v[204:207], v158 offset:20480
	ds_read_b128 v[208:211], v158 offset:21504
	ds_read_b128 v[212:215], v158 offset:22528
	ds_read_b128 v[216:219], v158 offset:23552
	s_waitcnt vmcnt(8)
	s_waitcnt lgkmcnt(0)
	s_barrier
	s_setprio 0
	s_waitcnt lgkmcnt(0)
	v_mfma_f32_16x16x32_bf16 v[60:63], v[146:149], v[188:191], v[60:63]
	v_mfma_f32_16x16x32_bf16 v[56:59], v[164:167], v[188:191], v[56:59]
	v_mfma_f32_16x16x32_bf16 v[44:47], v[146:149], v[196:199], v[44:47]
	v_mfma_f32_16x16x32_bf16 v[40:43], v[164:167], v[196:199], v[40:43]
	v_mfma_f32_16x16x32_bf16 v[28:31], v[146:149], v[204:207], v[28:31]
	v_mfma_f32_16x16x32_bf16 v[24:27], v[164:167], v[204:207], v[24:27]
	v_mfma_f32_16x16x32_bf16 v[12:15], v[146:149], v[212:215], v[12:15]
	v_mfma_f32_16x16x32_bf16 v[8:11], v[164:167], v[212:215], v[8:11]
	v_mfma_f32_16x16x32_bf16 v[60:63], v[160:163], v[192:195], v[60:63]
	v_mfma_f32_16x16x32_bf16 v[56:59], v[168:171], v[192:195], v[56:59]
	v_mfma_f32_16x16x32_bf16 v[44:47], v[160:163], v[200:203], v[44:47]
	v_mfma_f32_16x16x32_bf16 v[40:43], v[168:171], v[200:203], v[40:43]
	v_mfma_f32_16x16x32_bf16 v[28:31], v[160:163], v[208:211], v[28:31]
	v_mfma_f32_16x16x32_bf16 v[24:27], v[168:171], v[208:211], v[24:27]
	v_mfma_f32_16x16x32_bf16 v[12:15], v[160:163], v[216:219], v[12:15]
	v_mfma_f32_16x16x32_bf16 v[8:11], v[168:171], v[216:219], v[8:11]
	v_mfma_f32_16x16x32_bf16 v[52:55], v[172:175], v[188:191], v[52:55]
	v_mfma_f32_16x16x32_bf16 v[48:51], v[180:183], v[188:191], v[48:51]
	v_mfma_f32_16x16x32_bf16 v[36:39], v[172:175], v[196:199], v[36:39]
	v_mfma_f32_16x16x32_bf16 v[32:35], v[180:183], v[196:199], v[32:35]
	v_mfma_f32_16x16x32_bf16 v[20:23], v[172:175], v[204:207], v[20:23]
	v_mfma_f32_16x16x32_bf16 v[16:19], v[180:183], v[204:207], v[16:19]
	v_mfma_f32_16x16x32_bf16 v[4:7], v[172:175], v[212:215], v[4:7]
	v_mfma_f32_16x16x32_bf16 v[0:3], v[180:183], v[212:215], v[0:3]
	v_mfma_f32_16x16x32_bf16 v[52:55], v[176:179], v[192:195], v[52:55]
	v_mfma_f32_16x16x32_bf16 v[48:51], v[184:187], v[192:195], v[48:51]
	v_mfma_f32_16x16x32_bf16 v[36:39], v[176:179], v[200:203], v[36:39]
	v_mfma_f32_16x16x32_bf16 v[32:35], v[184:187], v[200:203], v[32:35]
	v_mfma_f32_16x16x32_bf16 v[20:23], v[176:179], v[208:211], v[20:23]
	v_mfma_f32_16x16x32_bf16 v[16:19], v[184:187], v[208:211], v[16:19]
	v_mfma_f32_16x16x32_bf16 v[4:7], v[176:179], v[216:219], v[4:7]
	v_mfma_f32_16x16x32_bf16 v[0:3], v[184:187], v[216:219], v[0:3]
	s_setprio 1
	s_barrier
	s_add_i32 s65, 0, 0x18000
	s_add_i32 s66, 0, 0x1c000
	v_add_u32_e32 v168, s65, v154
	v_add_u32_e32 v184, s66, v154
	ds_read_b128 v[146:149], v168
	ds_read_b128 v[160:163], v168 offset:1024
	ds_read_b128 v[164:167], v168 offset:2048
	ds_read_b128 v[168:171], v168 offset:3072
	ds_read_b128 v[172:175], v184
	ds_read_b128 v[176:179], v184 offset:1024
	ds_read_b128 v[180:183], v184 offset:2048
	ds_read_b128 v[184:187], v184 offset:3072
	s_add_u32 s36, s42, 0x80000
	s_addc_u32 s37, s43, 0
	s_mov_b32 m0, s48
	v_lshl_add_u64 v[188:189], s[36:37], 0, v[128:129]
	global_load_lds_dwordx4 v[188:189], off
	v_lshl_add_u64 v[188:189], s[36:37], 0, v[132:133]
	s_mov_b32 m0, s49
	s_nop 0
	global_load_lds_dwordx4 v[188:189], off
	ds_read_b128 v[188:191], v158 offset:32768
	ds_read_b128 v[192:195], v158 offset:33792
	ds_read_b128 v[196:199], v158 offset:34816
	ds_read_b128 v[200:203], v158 offset:35840
	ds_read_b128 v[204:207], v158 offset:36864
	ds_read_b128 v[208:211], v158 offset:37888
	ds_read_b128 v[212:215], v158 offset:38912
	ds_read_b128 v[216:219], v158 offset:39936
	s_waitcnt vmcnt(8)
	s_waitcnt lgkmcnt(0)
	s_barrier
	s_setprio 0
	s_waitcnt lgkmcnt(0)
	v_mfma_f32_16x16x32_bf16 v[124:127], v[146:149], v[188:191], v[124:127]
	v_mfma_f32_16x16x32_bf16 v[120:123], v[164:167], v[188:191], v[120:123]
	v_mfma_f32_16x16x32_bf16 v[108:111], v[146:149], v[196:199], v[108:111]
	v_mfma_f32_16x16x32_bf16 v[104:107], v[164:167], v[196:199], v[104:107]
	v_mfma_f32_16x16x32_bf16 v[92:95], v[146:149], v[204:207], v[92:95]
	v_mfma_f32_16x16x32_bf16 v[88:91], v[164:167], v[204:207], v[88:91]
	v_mfma_f32_16x16x32_bf16 v[76:79], v[146:149], v[212:215], v[76:79]
	v_mfma_f32_16x16x32_bf16 v[72:75], v[164:167], v[212:215], v[72:75]
	v_mfma_f32_16x16x32_bf16 v[124:127], v[160:163], v[192:195], v[124:127]
	v_mfma_f32_16x16x32_bf16 v[120:123], v[168:171], v[192:195], v[120:123]
	v_mfma_f32_16x16x32_bf16 v[108:111], v[160:163], v[200:203], v[108:111]
	v_mfma_f32_16x16x32_bf16 v[104:107], v[168:171], v[200:203], v[104:107]
	v_mfma_f32_16x16x32_bf16 v[92:95], v[160:163], v[208:211], v[92:95]
	v_mfma_f32_16x16x32_bf16 v[88:91], v[168:171], v[208:211], v[88:91]
	v_mfma_f32_16x16x32_bf16 v[76:79], v[160:163], v[216:219], v[76:79]
	v_mfma_f32_16x16x32_bf16 v[72:75], v[168:171], v[216:219], v[72:75]
	v_mfma_f32_16x16x32_bf16 v[116:119], v[172:175], v[188:191], v[116:119]
	v_mfma_f32_16x16x32_bf16 v[112:115], v[180:183], v[188:191], v[112:115]
	v_mfma_f32_16x16x32_bf16 v[100:103], v[172:175], v[196:199], v[100:103]
	v_mfma_f32_16x16x32_bf16 v[96:99], v[180:183], v[196:199], v[96:99]
	v_mfma_f32_16x16x32_bf16 v[84:87], v[172:175], v[204:207], v[84:87]
	v_mfma_f32_16x16x32_bf16 v[80:83], v[180:183], v[204:207], v[80:83]
	v_mfma_f32_16x16x32_bf16 v[68:71], v[172:175], v[212:215], v[68:71]
	v_mfma_f32_16x16x32_bf16 v[64:67], v[180:183], v[212:215], v[64:67]
	v_mfma_f32_16x16x32_bf16 v[116:119], v[176:179], v[192:195], v[116:119]
	v_mfma_f32_16x16x32_bf16 v[112:115], v[184:187], v[192:195], v[112:115]
	v_mfma_f32_16x16x32_bf16 v[100:103], v[176:179], v[200:203], v[100:103]
	v_mfma_f32_16x16x32_bf16 v[96:99], v[184:187], v[200:203], v[96:99]
	v_mfma_f32_16x16x32_bf16 v[84:87], v[176:179], v[208:211], v[84:87]
	v_mfma_f32_16x16x32_bf16 v[80:83], v[184:187], v[208:211], v[80:83]
	v_mfma_f32_16x16x32_bf16 v[68:71], v[176:179], v[216:219], v[68:71]
	v_mfma_f32_16x16x32_bf16 v[64:67], v[184:187], v[216:219], v[64:67]
	s_setprio 1
	s_barrier
	s_add_i32 s36, s65, s11
	v_lshl_add_u64 v[150:151], v[150:151], 0, s[14:15]
	s_mov_b32 m0, s36
	s_nop 0
	global_load_lds_dwordx4 v[150:151], off
	s_add_i32 m0, s36, 0x2000
	s_add_u32 s36, s40, 0x80080
	v_lshl_add_u64 v[150:151], v[220:221], 0, s[14:15]
	s_addc_u32 s37, s41, 0
	s_add_i32 s40, s66, s11
	global_load_lds_dwordx4 v[150:151], off
	v_lshl_add_u64 v[150:151], s[36:37], 0, v[130:131]
	s_mov_b32 m0, s40
	s_nop 0
	global_load_lds_dwordx4 v[150:151], off
	v_lshl_add_u64 v[150:151], s[36:37], 0, v[134:135]
	s_add_i32 m0, s40, 0x2000
	s_nop 0
	global_load_lds_dwordx4 v[150:151], off
	v_lshl_add_u64 v[150:151], v[222:223], 0, s[14:15]
	s_mov_b32 m0, s53
	s_nop 0
	global_load_lds_dwordx4 v[150:151], off
	v_lshl_add_u64 v[150:151], v[224:225], 0, s[14:15]
	s_mov_b32 m0, s54
	s_nop 0
	global_load_lds_dwordx4 v[150:151], off
	ds_read_b128 v[188:191], v158 offset:49152
	ds_read_b128 v[192:195], v158 offset:50176
	ds_read_b128 v[196:199], v158 offset:51200
	ds_read_b128 v[200:203], v158 offset:52224
	ds_read_b128 v[204:207], v158 offset:53248
	ds_read_b128 v[208:211], v158 offset:54272
	ds_read_b128 v[212:215], v158 offset:55296
	ds_read_b128 v[216:219], v158 offset:56320
	s_waitcnt vmcnt(8)
	s_waitcnt lgkmcnt(0)
	s_barrier
	s_setprio 0
	s_waitcnt lgkmcnt(0)
	v_mfma_f32_16x16x32_bf16 v[60:63], v[146:149], v[188:191], v[60:63]
	v_mfma_f32_16x16x32_bf16 v[56:59], v[164:167], v[188:191], v[56:59]
	v_mfma_f32_16x16x32_bf16 v[44:47], v[146:149], v[196:199], v[44:47]
	v_mfma_f32_16x16x32_bf16 v[40:43], v[164:167], v[196:199], v[40:43]
	v_mfma_f32_16x16x32_bf16 v[28:31], v[146:149], v[204:207], v[28:31]
	v_mfma_f32_16x16x32_bf16 v[24:27], v[164:167], v[204:207], v[24:27]
	v_mfma_f32_16x16x32_bf16 v[12:15], v[146:149], v[212:215], v[12:15]
	v_mfma_f32_16x16x32_bf16 v[8:11], v[164:167], v[212:215], v[8:11]
	v_mfma_f32_16x16x32_bf16 v[60:63], v[160:163], v[192:195], v[60:63]
	v_mfma_f32_16x16x32_bf16 v[56:59], v[168:171], v[192:195], v[56:59]
	v_mfma_f32_16x16x32_bf16 v[44:47], v[160:163], v[200:203], v[44:47]
	v_mfma_f32_16x16x32_bf16 v[40:43], v[168:171], v[200:203], v[40:43]
	v_mfma_f32_16x16x32_bf16 v[28:31], v[160:163], v[208:211], v[28:31]
	v_mfma_f32_16x16x32_bf16 v[24:27], v[168:171], v[208:211], v[24:27]
	v_mfma_f32_16x16x32_bf16 v[12:15], v[160:163], v[216:219], v[12:15]
	v_mfma_f32_16x16x32_bf16 v[8:11], v[168:171], v[216:219], v[8:11]
	v_mfma_f32_16x16x32_bf16 v[52:55], v[172:175], v[188:191], v[52:55]
	v_mfma_f32_16x16x32_bf16 v[48:51], v[180:183], v[188:191], v[48:51]
	v_mfma_f32_16x16x32_bf16 v[36:39], v[172:175], v[196:199], v[36:39]
	v_mfma_f32_16x16x32_bf16 v[32:35], v[180:183], v[196:199], v[32:35]
	v_mfma_f32_16x16x32_bf16 v[20:23], v[172:175], v[204:207], v[20:23]
	v_mfma_f32_16x16x32_bf16 v[16:19], v[180:183], v[204:207], v[16:19]
	v_mfma_f32_16x16x32_bf16 v[4:7], v[172:175], v[212:215], v[4:7]
	v_mfma_f32_16x16x32_bf16 v[0:3], v[180:183], v[212:215], v[0:3]
	v_mfma_f32_16x16x32_bf16 v[52:55], v[176:179], v[192:195], v[52:55]
	v_mfma_f32_16x16x32_bf16 v[48:51], v[184:187], v[192:195], v[48:51]
	v_mfma_f32_16x16x32_bf16 v[36:39], v[176:179], v[200:203], v[36:39]
	v_mfma_f32_16x16x32_bf16 v[32:35], v[184:187], v[200:203], v[32:35]
	v_mfma_f32_16x16x32_bf16 v[20:23], v[176:179], v[208:211], v[20:23]
	v_mfma_f32_16x16x32_bf16 v[16:19], v[184:187], v[208:211], v[16:19]
	v_mfma_f32_16x16x32_bf16 v[4:7], v[176:179], v[216:219], v[4:7]
	v_mfma_f32_16x16x32_bf16 v[0:3], v[184:187], v[216:219], v[0:3]
	s_setprio 1
	s_barrier
	s_add_i32 s64, s64, 2
	s_add_u32 s62, s62, 0x100
	s_addc_u32 s63, s63, 0
	s_cmp_gt_u32 s64, 29
	s_mov_b64 s[36:37], s[38:39]
	s_cbranch_scc0 .LBB0_387
	s_setprio 0
	s_and_b64 vcc, exec, s[4:5]
	s_cbranch_vccnz .LBB0_392
	s_cmp_gt_i32 s59, 11
	s_mov_b64 s[36:37], -1
	s_cbranch_scc1 .LBB0_393

.LBB0_1117:
	ds_read_b128 v[144:147], v159
	ds_read_b128 v[148:151], v159 offset:1024
	ds_read_b128 v[162:165], v159 offset:2048
	ds_read_b128 v[166:169], v159 offset:3072
	ds_read_b128 v[170:173], v160
	ds_read_b128 v[174:177], v160 offset:1024
	ds_read_b128 v[178:181], v160 offset:2048
	ds_read_b128 v[182:185], v160 offset:3072
	s_add_u32 s48, s46, 0xfff80080
	s_addc_u32 s49, s47, -1
	s_cmp_eq_u32 s63, 28
	s_cselect_b32 s51, s7, s49
	s_cselect_b32 s50, s11, s48
	s_cselect_b32 s49, s37, s62
	s_cselect_b32 s48, s39, s45
	v_lshl_add_u64 v[152:153], s[46:47], 0, v[136:137]
	s_add_i32 m0, s55, 0xc000
	s_nop 0
	global_load_lds_dwordx4 v[152:153], off
	v_lshl_add_u64 v[152:153], s[46:47], 0, v[138:139]
	s_add_i32 m0, s55, 0xe000
	s_nop 0
	global_load_lds_dwordx4 v[152:153], off
	ds_read_b128 v[186:189], v161
	ds_read_b128 v[190:193], v161 offset:1024
	ds_read_b128 v[194:197], v161 offset:2048
	ds_read_b128 v[198:201], v161 offset:3072
	ds_read_b128 v[202:205], v161 offset:4096
	ds_read_b128 v[206:209], v161 offset:5120
	ds_read_b128 v[210:213], v161 offset:6144
	ds_read_b128 v[214:217], v161 offset:7168
	s_waitcnt vmcnt(8)
	s_waitcnt lgkmcnt(0)
	s_barrier
	s_setprio 0
	s_waitcnt lgkmcnt(0)
	v_mfma_f32_16x16x32_bf16 v[124:127], v[144:147], v[186:189], v[124:127]
	v_mfma_f32_16x16x32_bf16 v[120:123], v[162:165], v[186:189], v[120:123]
	v_mfma_f32_16x16x32_bf16 v[108:111], v[144:147], v[194:197], v[108:111]
	v_mfma_f32_16x16x32_bf16 v[104:107], v[162:165], v[194:197], v[104:107]
	v_mfma_f32_16x16x32_bf16 v[92:95], v[144:147], v[202:205], v[92:95]
	v_mfma_f32_16x16x32_bf16 v[88:91], v[162:165], v[202:205], v[88:91]
	v_mfma_f32_16x16x32_bf16 v[76:79], v[144:147], v[210:213], v[76:79]
	v_mfma_f32_16x16x32_bf16 v[72:75], v[162:165], v[210:213], v[72:75]
	v_mfma_f32_16x16x32_bf16 v[124:127], v[148:151], v[190:193], v[124:127]
	v_mfma_f32_16x16x32_bf16 v[120:123], v[166:169], v[190:193], v[120:123]
	v_mfma_f32_16x16x32_bf16 v[108:111], v[148:151], v[198:201], v[108:111]
	v_mfma_f32_16x16x32_bf16 v[104:107], v[166:169], v[198:201], v[104:107]
	v_mfma_f32_16x16x32_bf16 v[92:95], v[148:151], v[206:209], v[92:95]
	v_mfma_f32_16x16x32_bf16 v[88:91], v[166:169], v[206:209], v[88:91]
	v_mfma_f32_16x16x32_bf16 v[76:79], v[148:151], v[214:217], v[76:79]
	v_mfma_f32_16x16x32_bf16 v[72:75], v[166:169], v[214:217], v[72:75]
	v_mfma_f32_16x16x32_bf16 v[116:119], v[170:173], v[186:189], v[116:119]
	v_mfma_f32_16x16x32_bf16 v[112:115], v[178:181], v[186:189], v[112:115]
	v_mfma_f32_16x16x32_bf16 v[100:103], v[170:173], v[194:197], v[100:103]
	v_mfma_f32_16x16x32_bf16 v[96:99], v[178:181], v[194:197], v[96:99]
	v_mfma_f32_16x16x32_bf16 v[84:87], v[170:173], v[202:205], v[84:87]
	v_mfma_f32_16x16x32_bf16 v[80:83], v[178:181], v[202:205], v[80:83]
	v_mfma_f32_16x16x32_bf16 v[68:71], v[170:173], v[210:213], v[68:71]
	v_mfma_f32_16x16x32_bf16 v[64:67], v[178:181], v[210:213], v[64:67]
	v_mfma_f32_16x16x32_bf16 v[116:119], v[174:177], v[190:193], v[116:119]
	v_mfma_f32_16x16x32_bf16 v[112:115], v[182:185], v[190:193], v[112:115]
	v_mfma_f32_16x16x32_bf16 v[100:103], v[174:177], v[198:201], v[100:103]
	v_mfma_f32_16x16x32_bf16 v[96:99], v[182:185], v[198:201], v[96:99]
	v_mfma_f32_16x16x32_bf16 v[84:87], v[174:177], v[206:209], v[84:87]
	v_mfma_f32_16x16x32_bf16 v[80:83], v[182:185], v[206:209], v[80:83]
	v_mfma_f32_16x16x32_bf16 v[68:71], v[174:177], v[214:217], v[68:71]
	v_mfma_f32_16x16x32_bf16 v[64:67], v[182:185], v[214:217], v[64:67]
	s_setprio 1
	s_barrier
	s_add_i32 s64, s60, s21
	v_lshl_add_u64 v[152:153], s[48:49], 0, v[130:131]
	s_mov_b32 m0, s64
	v_lshl_add_u64 v[218:219], s[48:49], 0, v[134:135]
	global_load_lds_dwordx4 v[152:153], off
	s_add_i32 m0, s64, 0x2000
	s_add_u32 s64, s48, 0x80000
	s_addc_u32 s65, s49, 0
	s_add_i32 s66, s61, s21
	global_load_lds_dwordx4 v[218:219], off
	v_lshl_add_u64 v[186:187], s[64:65], 0, v[130:131]
	s_mov_b32 m0, s66
	v_lshl_add_u64 v[220:221], s[50:51], 0, v[128:129]
	global_load_lds_dwordx4 v[186:187], off
	v_lshl_add_u64 v[186:187], s[64:65], 0, v[134:135]
	s_add_i32 m0, s66, 0x2000
	v_lshl_add_u64 v[222:223], s[50:51], 0, v[132:133]
	global_load_lds_dwordx4 v[186:187], off
	s_mov_b32 m0, s55
	s_nop 0
	global_load_lds_dwordx4 v[220:221], off
	s_mov_b32 m0, s56
	s_nop 0
	global_load_lds_dwordx4 v[222:223], off
	ds_read_b128 v[186:189], v161 offset:16384
	ds_read_b128 v[190:193], v161 offset:17408
	ds_read_b128 v[194:197], v161 offset:18432
	ds_read_b128 v[198:201], v161 offset:19456
	ds_read_b128 v[202:205], v161 offset:20480
	ds_read_b128 v[206:209], v161 offset:21504
	ds_read_b128 v[210:213], v161 offset:22528
	ds_read_b128 v[214:217], v161 offset:23552
	s_waitcnt vmcnt(8)
	s_waitcnt lgkmcnt(0)
	s_barrier
	s_setprio 0
	s_waitcnt lgkmcnt(0)
	v_mfma_f32_16x16x32_bf16 v[60:63], v[144:147], v[186:189], v[60:63]
	v_mfma_f32_16x16x32_bf16 v[56:59], v[162:165], v[186:189], v[56:59]
	v_mfma_f32_16x16x32_bf16 v[44:47], v[144:147], v[194:197], v[44:47]
	v_mfma_f32_16x16x32_bf16 v[40:43], v[162:165], v[194:197], v[40:43]
	v_mfma_f32_16x16x32_bf16 v[28:31], v[144:147], v[202:205], v[28:31]
	v_mfma_f32_16x16x32_bf16 v[24:27], v[162:165], v[202:205], v[24:27]
	v_mfma_f32_16x16x32_bf16 v[12:15], v[144:147], v[210:213], v[12:15]
	v_mfma_f32_16x16x32_bf16 v[8:11], v[162:165], v[210:213], v[8:11]
	v_mfma_f32_16x16x32_bf16 v[60:63], v[148:151], v[190:193], v[60:63]
	v_mfma_f32_16x16x32_bf16 v[56:59], v[166:169], v[190:193], v[56:59]
	v_mfma_f32_16x16x32_bf16 v[44:47], v[148:151], v[198:201], v[44:47]
	v_mfma_f32_16x16x32_bf16 v[40:43], v[166:169], v[198:201], v[40:43]
	v_mfma_f32_16x16x32_bf16 v[28:31], v[148:151], v[206:209], v[28:31]
	v_mfma_f32_16x16x32_bf16 v[24:27], v[166:169], v[206:209], v[24:27]
	v_mfma_f32_16x16x32_bf16 v[12:15], v[148:151], v[214:217], v[12:15]
	v_mfma_f32_16x16x32_bf16 v[8:11], v[166:169], v[214:217], v[8:11]
	v_mfma_f32_16x16x32_bf16 v[52:55], v[170:173], v[186:189], v[52:55]
	v_mfma_f32_16x16x32_bf16 v[48:51], v[178:181], v[186:189], v[48:51]
	v_mfma_f32_16x16x32_bf16 v[36:39], v[170:173], v[194:197], v[36:39]
	v_mfma_f32_16x16x32_bf16 v[32:35], v[178:181], v[194:197], v[32:35]
	v_mfma_f32_16x16x32_bf16 v[20:23], v[170:173], v[202:205], v[20:23]
	v_mfma_f32_16x16x32_bf16 v[16:19], v[178:181], v[202:205], v[16:19]
	v_mfma_f32_16x16x32_bf16 v[4:7], v[170:173], v[210:213], v[4:7]
	v_mfma_f32_16x16x32_bf16 v[0:3], v[178:181], v[210:213], v[0:3]
	v_mfma_f32_16x16x32_bf16 v[52:55], v[174:177], v[190:193], v[52:55]
	v_mfma_f32_16x16x32_bf16 v[48:51], v[182:185], v[190:193], v[48:51]
	v_mfma_f32_16x16x32_bf16 v[36:39], v[174:177], v[198:201], v[36:39]
	v_mfma_f32_16x16x32_bf16 v[32:35], v[182:185], v[198:201], v[32:35]
	v_mfma_f32_16x16x32_bf16 v[20:23], v[174:177], v[206:209], v[20:23]
	v_mfma_f32_16x16x32_bf16 v[16:19], v[182:185], v[206:209], v[16:19]
	v_mfma_f32_16x16x32_bf16 v[4:7], v[174:177], v[214:217], v[4:7]
	v_mfma_f32_16x16x32_bf16 v[0:3], v[182:185], v[214:217], v[0:3]
	s_setprio 1
	s_barrier
	s_add_i32 s64, 0, 0x18000
	s_add_i32 s65, 0, 0x1c000
	v_add_u32_e32 v166, s64, v154
	v_add_u32_e32 v182, s65, v154
	ds_read_b128 v[144:147], v166
	ds_read_b128 v[148:151], v166 offset:1024
	ds_read_b128 v[162:165], v166 offset:2048
	ds_read_b128 v[166:169], v166 offset:3072
	ds_read_b128 v[170:173], v182
	ds_read_b128 v[174:177], v182 offset:1024
	ds_read_b128 v[178:181], v182 offset:2048
	ds_read_b128 v[182:185], v182 offset:3072
	s_add_u32 s50, s50, 0x80000
	s_addc_u32 s51, s51, 0
	s_mov_b32 m0, s57
	v_lshl_add_u64 v[186:187], s[50:51], 0, v[128:129]
	global_load_lds_dwordx4 v[186:187], off
	v_lshl_add_u64 v[186:187], s[50:51], 0, v[132:133]
	s_mov_b32 m0, s58
	s_nop 0
	global_load_lds_dwordx4 v[186:187], off
	ds_read_b128 v[186:189], v161 offset:32768
	ds_read_b128 v[190:193], v161 offset:33792
	ds_read_b128 v[194:197], v161 offset:34816
	ds_read_b128 v[198:201], v161 offset:35840
	ds_read_b128 v[202:205], v161 offset:36864
	ds_read_b128 v[206:209], v161 offset:37888
	ds_read_b128 v[210:213], v161 offset:38912
	ds_read_b128 v[214:217], v161 offset:39936
	s_waitcnt vmcnt(8)
	s_waitcnt lgkmcnt(0)
	s_barrier
	s_setprio 0
	s_waitcnt lgkmcnt(0)
	v_mfma_f32_16x16x32_bf16 v[124:127], v[144:147], v[186:189], v[124:127]
	v_mfma_f32_16x16x32_bf16 v[120:123], v[162:165], v[186:189], v[120:123]
	v_mfma_f32_16x16x32_bf16 v[108:111], v[144:147], v[194:197], v[108:111]
	v_mfma_f32_16x16x32_bf16 v[104:107], v[162:165], v[194:197], v[104:107]
	v_mfma_f32_16x16x32_bf16 v[92:95], v[144:147], v[202:205], v[92:95]
	v_mfma_f32_16x16x32_bf16 v[88:91], v[162:165], v[202:205], v[88:91]
	v_mfma_f32_16x16x32_bf16 v[76:79], v[144:147], v[210:213], v[76:79]
	v_mfma_f32_16x16x32_bf16 v[72:75], v[162:165], v[210:213], v[72:75]
	v_mfma_f32_16x16x32_bf16 v[124:127], v[148:151], v[190:193], v[124:127]
	v_mfma_f32_16x16x32_bf16 v[120:123], v[166:169], v[190:193], v[120:123]
	v_mfma_f32_16x16x32_bf16 v[108:111], v[148:151], v[198:201], v[108:111]
	v_mfma_f32_16x16x32_bf16 v[104:107], v[166:169], v[198:201], v[104:107]
	v_mfma_f32_16x16x32_bf16 v[92:95], v[148:151], v[206:209], v[92:95]
	v_mfma_f32_16x16x32_bf16 v[88:91], v[166:169], v[206:209], v[88:91]
	v_mfma_f32_16x16x32_bf16 v[76:79], v[148:151], v[214:217], v[76:79]
	v_mfma_f32_16x16x32_bf16 v[72:75], v[166:169], v[214:217], v[72:75]
	v_mfma_f32_16x16x32_bf16 v[116:119], v[170:173], v[186:189], v[116:119]
	v_mfma_f32_16x16x32_bf16 v[112:115], v[178:181], v[186:189], v[112:115]
	v_mfma_f32_16x16x32_bf16 v[100:103], v[170:173], v[194:197], v[100:103]
	v_mfma_f32_16x16x32_bf16 v[96:99], v[178:181], v[194:197], v[96:99]
	v_mfma_f32_16x16x32_bf16 v[84:87], v[170:173], v[202:205], v[84:87]
	v_mfma_f32_16x16x32_bf16 v[80:83], v[178:181], v[202:205], v[80:83]
	v_mfma_f32_16x16x32_bf16 v[68:71], v[170:173], v[210:213], v[68:71]
	v_mfma_f32_16x16x32_bf16 v[64:67], v[178:181], v[210:213], v[64:67]
	v_mfma_f32_16x16x32_bf16 v[116:119], v[174:177], v[190:193], v[116:119]
	v_mfma_f32_16x16x32_bf16 v[112:115], v[182:185], v[190:193], v[112:115]
	v_mfma_f32_16x16x32_bf16 v[100:103], v[174:177], v[198:201], v[100:103]
	v_mfma_f32_16x16x32_bf16 v[96:99], v[182:185], v[198:201], v[96:99]
	v_mfma_f32_16x16x32_bf16 v[84:87], v[174:177], v[206:209], v[84:87]
	v_mfma_f32_16x16x32_bf16 v[80:83], v[182:185], v[206:209], v[80:83]
	v_mfma_f32_16x16x32_bf16 v[68:71], v[174:177], v[214:217], v[68:71]
	v_mfma_f32_16x16x32_bf16 v[64:67], v[182:185], v[214:217], v[64:67]
	s_setprio 1
	s_barrier
	s_add_i32 s50, s64, s21
	v_lshl_add_u64 v[152:153], v[152:153], 0, s[30:31]
	s_mov_b32 m0, s50
	s_nop 0
	global_load_lds_dwordx4 v[152:153], off
	s_add_i32 m0, s50, 0x2000
	s_add_u32 s48, s48, 0x80080
	v_lshl_add_u64 v[152:153], v[218:219], 0, s[30:31]
	s_addc_u32 s49, s49, 0
	s_add_i32 s50, s65, s21
	global_load_lds_dwordx4 v[152:153], off
	v_lshl_add_u64 v[152:153], s[48:49], 0, v[130:131]
	s_mov_b32 m0, s50
	s_nop 0
	global_load_lds_dwordx4 v[152:153], off
	v_lshl_add_u64 v[152:153], s[48:49], 0, v[134:135]
	s_add_i32 m0, s50, 0x2000
	s_nop 0
	global_load_lds_dwordx4 v[152:153], off
	v_lshl_add_u64 v[152:153], v[220:221], 0, s[30:31]
	s_mov_b32 m0, s26
	s_nop 0
	global_load_lds_dwordx4 v[152:153], off
	v_lshl_add_u64 v[152:153], v[222:223], 0, s[30:31]
	s_mov_b32 m0, s27
	s_nop 0
	global_load_lds_dwordx4 v[152:153], off
	ds_read_b128 v[186:189], v161 offset:49152
	ds_read_b128 v[190:193], v161 offset:50176
	ds_read_b128 v[194:197], v161 offset:51200
	ds_read_b128 v[198:201], v161 offset:52224
	ds_read_b128 v[202:205], v161 offset:53248
	ds_read_b128 v[206:209], v161 offset:54272
	ds_read_b128 v[210:213], v161 offset:55296
	ds_read_b128 v[214:217], v161 offset:56320
	s_waitcnt vmcnt(8)
	s_waitcnt lgkmcnt(0)
	s_barrier
	s_setprio 0
	s_waitcnt lgkmcnt(0)
	v_mfma_f32_16x16x32_bf16 v[60:63], v[144:147], v[186:189], v[60:63]
	v_mfma_f32_16x16x32_bf16 v[56:59], v[162:165], v[186:189], v[56:59]
	v_mfma_f32_16x16x32_bf16 v[44:47], v[144:147], v[194:197], v[44:47]
	v_mfma_f32_16x16x32_bf16 v[40:43], v[162:165], v[194:197], v[40:43]
	v_mfma_f32_16x16x32_bf16 v[28:31], v[144:147], v[202:205], v[28:31]
	v_mfma_f32_16x16x32_bf16 v[24:27], v[162:165], v[202:205], v[24:27]
	v_mfma_f32_16x16x32_bf16 v[12:15], v[144:147], v[210:213], v[12:15]
	v_mfma_f32_16x16x32_bf16 v[8:11], v[162:165], v[210:213], v[8:11]
	v_mfma_f32_16x16x32_bf16 v[60:63], v[148:151], v[190:193], v[60:63]
	v_mfma_f32_16x16x32_bf16 v[56:59], v[166:169], v[190:193], v[56:59]
	v_mfma_f32_16x16x32_bf16 v[44:47], v[148:151], v[198:201], v[44:47]
	v_mfma_f32_16x16x32_bf16 v[40:43], v[166:169], v[198:201], v[40:43]
	v_mfma_f32_16x16x32_bf16 v[28:31], v[148:151], v[206:209], v[28:31]
	v_mfma_f32_16x16x32_bf16 v[24:27], v[166:169], v[206:209], v[24:27]
	v_mfma_f32_16x16x32_bf16 v[12:15], v[148:151], v[214:217], v[12:15]
	v_mfma_f32_16x16x32_bf16 v[8:11], v[166:169], v[214:217], v[8:11]
	v_mfma_f32_16x16x32_bf16 v[52:55], v[170:173], v[186:189], v[52:55]
	v_mfma_f32_16x16x32_bf16 v[48:51], v[178:181], v[186:189], v[48:51]
	v_mfma_f32_16x16x32_bf16 v[36:39], v[170:173], v[194:197], v[36:39]
	v_mfma_f32_16x16x32_bf16 v[32:35], v[178:181], v[194:197], v[32:35]
	v_mfma_f32_16x16x32_bf16 v[20:23], v[170:173], v[202:205], v[20:23]
	v_mfma_f32_16x16x32_bf16 v[16:19], v[178:181], v[202:205], v[16:19]
	v_mfma_f32_16x16x32_bf16 v[4:7], v[170:173], v[210:213], v[4:7]
	v_mfma_f32_16x16x32_bf16 v[0:3], v[178:181], v[210:213], v[0:3]
	v_mfma_f32_16x16x32_bf16 v[52:55], v[174:177], v[190:193], v[52:55]
	v_mfma_f32_16x16x32_bf16 v[48:51], v[182:185], v[190:193], v[48:51]
	v_mfma_f32_16x16x32_bf16 v[36:39], v[174:177], v[198:201], v[36:39]
	v_mfma_f32_16x16x32_bf16 v[32:35], v[182:185], v[198:201], v[32:35]
	v_mfma_f32_16x16x32_bf16 v[20:23], v[174:177], v[206:209], v[20:23]
	v_mfma_f32_16x16x32_bf16 v[16:19], v[182:185], v[206:209], v[16:19]
	v_mfma_f32_16x16x32_bf16 v[4:7], v[174:177], v[214:217], v[4:7]
	v_mfma_f32_16x16x32_bf16 v[0:3], v[182:185], v[214:217], v[0:3]
	s_setprio 1
	s_barrier
	s_add_i32 s63, s63, 2
	s_add_u32 s46, s46, 0x100
	s_addc_u32 s47, s47, 0
	s_add_u32 s45, s45, 0x100
	s_addc_u32 s62, s62, 0
	s_cmp_gt_u32 s63, 29
	s_cbranch_scc0 .LBB0_1117
	s_setprio 0
	s_and_b64 vcc, exec, s[16:17]
	s_cbranch_vccz .LBB0_1120
	s_barrier

.LBB0_1240:
	ds_read_b128 v[144:147], v153
	ds_read_b128 v[158:161], v153 offset:1024
	ds_read_b128 v[162:165], v153 offset:2048
	ds_read_b128 v[166:169], v153 offset:3072
	ds_read_b128 v[170:173], v154
	ds_read_b128 v[174:177], v154 offset:1024
	ds_read_b128 v[178:181], v154 offset:2048
	ds_read_b128 v[182:185], v154 offset:3072
	s_add_u32 s40, s38, 0x100
	s_addc_u32 s41, s39, 0
	s_cmp_eq_u32 s61, 28
	s_cselect_b32 s45, s29, s41
	s_cselect_b32 s44, s57, s40
	s_cselect_b32 s43, s19, s60
	s_cselect_b32 s42, s58, s59
	v_lshl_add_u64 v[148:149], s[38:39], 0, v[136:137]
	s_add_i32 m0, s37, 0xc000
	s_nop 0
	global_load_lds_dwordx4 v[148:149], off
	v_lshl_add_u64 v[148:149], s[38:39], 0, v[138:139]
	s_add_i32 m0, s37, 0xe000
	s_nop 0
	global_load_lds_dwordx4 v[148:149], off
	ds_read_b128 v[186:189], v155
	ds_read_b128 v[190:193], v155 offset:1024
	ds_read_b128 v[194:197], v155 offset:2048
	ds_read_b128 v[198:201], v155 offset:3072
	ds_read_b128 v[202:205], v155 offset:4096
	ds_read_b128 v[206:209], v155 offset:5120
	ds_read_b128 v[210:213], v155 offset:6144
	ds_read_b128 v[214:217], v155 offset:7168
	s_waitcnt vmcnt(8)
	s_waitcnt lgkmcnt(0)
	s_barrier
	s_setprio 0
	s_waitcnt lgkmcnt(0)
	v_mfma_f32_16x16x32_bf16 v[124:127], v[144:147], v[186:189], v[124:127]
	v_mfma_f32_16x16x32_bf16 v[120:123], v[162:165], v[186:189], v[120:123]
	v_mfma_f32_16x16x32_bf16 v[108:111], v[144:147], v[194:197], v[108:111]
	v_mfma_f32_16x16x32_bf16 v[104:107], v[162:165], v[194:197], v[104:107]
	v_mfma_f32_16x16x32_bf16 v[92:95], v[144:147], v[202:205], v[92:95]
	v_mfma_f32_16x16x32_bf16 v[88:91], v[162:165], v[202:205], v[88:91]
	v_mfma_f32_16x16x32_bf16 v[76:79], v[144:147], v[210:213], v[76:79]
	v_mfma_f32_16x16x32_bf16 v[72:75], v[162:165], v[210:213], v[72:75]
	v_mfma_f32_16x16x32_bf16 v[124:127], v[158:161], v[190:193], v[124:127]
	v_mfma_f32_16x16x32_bf16 v[120:123], v[166:169], v[190:193], v[120:123]
	v_mfma_f32_16x16x32_bf16 v[108:111], v[158:161], v[198:201], v[108:111]
	v_mfma_f32_16x16x32_bf16 v[104:107], v[166:169], v[198:201], v[104:107]
	v_mfma_f32_16x16x32_bf16 v[92:95], v[158:161], v[206:209], v[92:95]
	v_mfma_f32_16x16x32_bf16 v[88:91], v[166:169], v[206:209], v[88:91]
	v_mfma_f32_16x16x32_bf16 v[76:79], v[158:161], v[214:217], v[76:79]
	v_mfma_f32_16x16x32_bf16 v[72:75], v[166:169], v[214:217], v[72:75]
	v_mfma_f32_16x16x32_bf16 v[116:119], v[170:173], v[186:189], v[116:119]
	v_mfma_f32_16x16x32_bf16 v[112:115], v[178:181], v[186:189], v[112:115]
	v_mfma_f32_16x16x32_bf16 v[100:103], v[170:173], v[194:197], v[100:103]
	v_mfma_f32_16x16x32_bf16 v[96:99], v[178:181], v[194:197], v[96:99]
	v_mfma_f32_16x16x32_bf16 v[84:87], v[170:173], v[202:205], v[84:87]
	v_mfma_f32_16x16x32_bf16 v[80:83], v[178:181], v[202:205], v[80:83]
	v_mfma_f32_16x16x32_bf16 v[68:71], v[170:173], v[210:213], v[68:71]
	v_mfma_f32_16x16x32_bf16 v[64:67], v[178:181], v[210:213], v[64:67]
	v_mfma_f32_16x16x32_bf16 v[116:119], v[174:177], v[190:193], v[116:119]
	v_mfma_f32_16x16x32_bf16 v[112:115], v[182:185], v[190:193], v[112:115]
	v_mfma_f32_16x16x32_bf16 v[100:103], v[174:177], v[198:201], v[100:103]
	v_mfma_f32_16x16x32_bf16 v[96:99], v[182:185], v[198:201], v[96:99]
	v_mfma_f32_16x16x32_bf16 v[84:87], v[174:177], v[206:209], v[84:87]
	v_mfma_f32_16x16x32_bf16 v[80:83], v[182:185], v[206:209], v[80:83]
	v_mfma_f32_16x16x32_bf16 v[68:71], v[174:177], v[214:217], v[68:71]
	v_mfma_f32_16x16x32_bf16 v[64:67], v[182:185], v[214:217], v[64:67]
	s_setprio 1
	s_barrier
	s_add_i32 s38, s54, s21
	v_lshl_add_u64 v[148:149], s[42:43], 0, v[132:133]
	s_mov_b32 m0, s38
	v_lshl_add_u64 v[218:219], s[42:43], 0, v[128:129]
	global_load_lds_dwordx4 v[148:149], off
	s_add_i32 m0, s38, 0x2000
	s_add_u32 s38, s42, 0x80000
	s_addc_u32 s39, s43, 0
	s_add_i32 s62, s55, s21
	global_load_lds_dwordx4 v[218:219], off
	v_lshl_add_u64 v[186:187], s[38:39], 0, v[132:133]
	s_mov_b32 m0, s62
	v_lshl_add_u64 v[220:221], s[44:45], 0, v[134:135]
	global_load_lds_dwordx4 v[186:187], off
	v_lshl_add_u64 v[186:187], s[38:39], 0, v[128:129]
	s_add_i32 m0, s62, 0x2000
	v_lshl_add_u64 v[222:223], s[44:45], 0, v[130:131]
	global_load_lds_dwordx4 v[186:187], off
	s_mov_b32 m0, s37
	s_nop 0
	global_load_lds_dwordx4 v[220:221], off
	s_mov_b32 m0, s47
	s_nop 0
	global_load_lds_dwordx4 v[222:223], off
	ds_read_b128 v[186:189], v155 offset:16384
	ds_read_b128 v[190:193], v155 offset:17408
	ds_read_b128 v[194:197], v155 offset:18432
	ds_read_b128 v[198:201], v155 offset:19456
	ds_read_b128 v[202:205], v155 offset:20480
	ds_read_b128 v[206:209], v155 offset:21504
	ds_read_b128 v[210:213], v155 offset:22528
	ds_read_b128 v[214:217], v155 offset:23552
	s_waitcnt vmcnt(8)
	s_waitcnt lgkmcnt(0)
	s_barrier
	s_setprio 0
	s_waitcnt lgkmcnt(0)
	v_mfma_f32_16x16x32_bf16 v[60:63], v[144:147], v[186:189], v[60:63]
	v_mfma_f32_16x16x32_bf16 v[56:59], v[162:165], v[186:189], v[56:59]
	v_mfma_f32_16x16x32_bf16 v[44:47], v[144:147], v[194:197], v[44:47]
	v_mfma_f32_16x16x32_bf16 v[40:43], v[162:165], v[194:197], v[40:43]
	v_mfma_f32_16x16x32_bf16 v[28:31], v[144:147], v[202:205], v[28:31]
	v_mfma_f32_16x16x32_bf16 v[24:27], v[162:165], v[202:205], v[24:27]
	v_mfma_f32_16x16x32_bf16 v[12:15], v[144:147], v[210:213], v[12:15]
	v_mfma_f32_16x16x32_bf16 v[8:11], v[162:165], v[210:213], v[8:11]
	v_mfma_f32_16x16x32_bf16 v[60:63], v[158:161], v[190:193], v[60:63]
	v_mfma_f32_16x16x32_bf16 v[56:59], v[166:169], v[190:193], v[56:59]
	v_mfma_f32_16x16x32_bf16 v[44:47], v[158:161], v[198:201], v[44:47]
	v_mfma_f32_16x16x32_bf16 v[40:43], v[166:169], v[198:201], v[40:43]
	v_mfma_f32_16x16x32_bf16 v[28:31], v[158:161], v[206:209], v[28:31]
	v_mfma_f32_16x16x32_bf16 v[24:27], v[166:169], v[206:209], v[24:27]
	v_mfma_f32_16x16x32_bf16 v[12:15], v[158:161], v[214:217], v[12:15]
	v_mfma_f32_16x16x32_bf16 v[8:11], v[166:169], v[214:217], v[8:11]
	v_mfma_f32_16x16x32_bf16 v[52:55], v[170:173], v[186:189], v[52:55]
	v_mfma_f32_16x16x32_bf16 v[48:51], v[178:181], v[186:189], v[48:51]
	v_mfma_f32_16x16x32_bf16 v[36:39], v[170:173], v[194:197], v[36:39]
	v_mfma_f32_16x16x32_bf16 v[32:35], v[178:181], v[194:197], v[32:35]
	v_mfma_f32_16x16x32_bf16 v[20:23], v[170:173], v[202:205], v[20:23]
	v_mfma_f32_16x16x32_bf16 v[16:19], v[178:181], v[202:205], v[16:19]
	v_mfma_f32_16x16x32_bf16 v[4:7], v[170:173], v[210:213], v[4:7]
	v_mfma_f32_16x16x32_bf16 v[0:3], v[178:181], v[210:213], v[0:3]
	v_mfma_f32_16x16x32_bf16 v[52:55], v[174:177], v[190:193], v[52:55]
	v_mfma_f32_16x16x32_bf16 v[48:51], v[182:185], v[190:193], v[48:51]
	v_mfma_f32_16x16x32_bf16 v[36:39], v[174:177], v[198:201], v[36:39]
	v_mfma_f32_16x16x32_bf16 v[32:35], v[182:185], v[198:201], v[32:35]
	v_mfma_f32_16x16x32_bf16 v[20:23], v[174:177], v[206:209], v[20:23]
	v_mfma_f32_16x16x32_bf16 v[16:19], v[182:185], v[206:209], v[16:19]
	v_mfma_f32_16x16x32_bf16 v[4:7], v[174:177], v[214:217], v[4:7]
	v_mfma_f32_16x16x32_bf16 v[0:3], v[182:185], v[214:217], v[0:3]
	s_setprio 1
	s_barrier
	s_add_i32 s62, 0, 0x18000
	v_add_u32_e32 v157, s62, v150
	s_add_i32 s63, 0, 0x1c000
	ds_read_b128 v[144:147], v157
	ds_read_b128 v[158:161], v157 offset:1024
	ds_read_b128 v[162:165], v157 offset:2048
	ds_read_b128 v[166:169], v157 offset:3072
	v_add_u32_e32 v157, s63, v150
	ds_read_b128 v[170:173], v157
	ds_read_b128 v[174:177], v157 offset:1024
	ds_read_b128 v[178:181], v157 offset:2048
	ds_read_b128 v[182:185], v157 offset:3072
	s_add_u32 s38, s44, 0x80000
	s_addc_u32 s39, s45, 0
	s_mov_b32 m0, s48
	v_lshl_add_u64 v[186:187], s[38:39], 0, v[134:135]
	global_load_lds_dwordx4 v[186:187], off
	v_lshl_add_u64 v[186:187], s[38:39], 0, v[130:131]
	s_mov_b32 m0, s49
	s_nop 0
	global_load_lds_dwordx4 v[186:187], off
	ds_read_b128 v[186:189], v155 offset:32768
	ds_read_b128 v[190:193], v155 offset:33792
	ds_read_b128 v[194:197], v155 offset:34816
	ds_read_b128 v[198:201], v155 offset:35840
	ds_read_b128 v[202:205], v155 offset:36864
	ds_read_b128 v[206:209], v155 offset:37888
	ds_read_b128 v[210:213], v155 offset:38912
	ds_read_b128 v[214:217], v155 offset:39936
	s_waitcnt vmcnt(8)
	s_waitcnt lgkmcnt(0)
	s_barrier
	s_setprio 0
	s_waitcnt lgkmcnt(0)
	v_mfma_f32_16x16x32_bf16 v[124:127], v[144:147], v[186:189], v[124:127]
	v_mfma_f32_16x16x32_bf16 v[120:123], v[162:165], v[186:189], v[120:123]
	v_mfma_f32_16x16x32_bf16 v[108:111], v[144:147], v[194:197], v[108:111]
	v_mfma_f32_16x16x32_bf16 v[104:107], v[162:165], v[194:197], v[104:107]
	v_mfma_f32_16x16x32_bf16 v[92:95], v[144:147], v[202:205], v[92:95]
	v_mfma_f32_16x16x32_bf16 v[88:91], v[162:165], v[202:205], v[88:91]
	v_mfma_f32_16x16x32_bf16 v[76:79], v[144:147], v[210:213], v[76:79]
	v_mfma_f32_16x16x32_bf16 v[72:75], v[162:165], v[210:213], v[72:75]
	v_mfma_f32_16x16x32_bf16 v[124:127], v[158:161], v[190:193], v[124:127]
	v_mfma_f32_16x16x32_bf16 v[120:123], v[166:169], v[190:193], v[120:123]
	v_mfma_f32_16x16x32_bf16 v[108:111], v[158:161], v[198:201], v[108:111]
	v_mfma_f32_16x16x32_bf16 v[104:107], v[166:169], v[198:201], v[104:107]
	v_mfma_f32_16x16x32_bf16 v[92:95], v[158:161], v[206:209], v[92:95]
	v_mfma_f32_16x16x32_bf16 v[88:91], v[166:169], v[206:209], v[88:91]
	v_mfma_f32_16x16x32_bf16 v[76:79], v[158:161], v[214:217], v[76:79]
	v_mfma_f32_16x16x32_bf16 v[72:75], v[166:169], v[214:217], v[72:75]
	v_mfma_f32_16x16x32_bf16 v[116:119], v[170:173], v[186:189], v[116:119]
	v_mfma_f32_16x16x32_bf16 v[112:115], v[178:181], v[186:189], v[112:115]
	v_mfma_f32_16x16x32_bf16 v[100:103], v[170:173], v[194:197], v[100:103]
	v_mfma_f32_16x16x32_bf16 v[96:99], v[178:181], v[194:197], v[96:99]
	v_mfma_f32_16x16x32_bf16 v[84:87], v[170:173], v[202:205], v[84:87]
	v_mfma_f32_16x16x32_bf16 v[80:83], v[178:181], v[202:205], v[80:83]
	v_mfma_f32_16x16x32_bf16 v[68:71], v[170:173], v[210:213], v[68:71]
	v_mfma_f32_16x16x32_bf16 v[64:67], v[178:181], v[210:213], v[64:67]
	v_mfma_f32_16x16x32_bf16 v[116:119], v[174:177], v[190:193], v[116:119]
	v_mfma_f32_16x16x32_bf16 v[112:115], v[182:185], v[190:193], v[112:115]
	v_mfma_f32_16x16x32_bf16 v[100:103], v[174:177], v[198:201], v[100:103]
	v_mfma_f32_16x16x32_bf16 v[96:99], v[182:185], v[198:201], v[96:99]
	v_mfma_f32_16x16x32_bf16 v[84:87], v[174:177], v[206:209], v[84:87]
	v_mfma_f32_16x16x32_bf16 v[80:83], v[182:185], v[206:209], v[80:83]
	v_mfma_f32_16x16x32_bf16 v[68:71], v[174:177], v[214:217], v[68:71]
	v_mfma_f32_16x16x32_bf16 v[64:67], v[182:185], v[214:217], v[64:67]
	s_setprio 1
	s_barrier
	s_add_i32 s38, s62, s21
	v_lshl_add_u64 v[148:149], v[148:149], 0, s[16:17]
	s_mov_b32 m0, s38
	s_nop 0
	global_load_lds_dwordx4 v[148:149], off
	s_add_i32 m0, s38, 0x2000
	s_add_u32 s38, s42, 0x80080
	v_lshl_add_u64 v[148:149], v[218:219], 0, s[16:17]
	s_addc_u32 s39, s43, 0
	s_add_i32 s42, s63, s21
	global_load_lds_dwordx4 v[148:149], off
	v_lshl_add_u64 v[148:149], s[38:39], 0, v[132:133]
	s_mov_b32 m0, s42
	s_nop 0
	global_load_lds_dwordx4 v[148:149], off
	v_lshl_add_u64 v[148:149], s[38:39], 0, v[128:129]
	s_add_i32 m0, s42, 0x2000
	s_nop 0
	global_load_lds_dwordx4 v[148:149], off
	v_lshl_add_u64 v[148:149], v[220:221], 0, s[16:17]
	s_mov_b32 m0, s51
	s_nop 0
	global_load_lds_dwordx4 v[148:149], off
	v_lshl_add_u64 v[148:149], v[222:223], 0, s[16:17]
	s_mov_b32 m0, s52
	s_nop 0
	global_load_lds_dwordx4 v[148:149], off
	ds_read_b128 v[186:189], v155 offset:49152
	ds_read_b128 v[190:193], v155 offset:50176
	ds_read_b128 v[194:197], v155 offset:51200
	ds_read_b128 v[198:201], v155 offset:52224
	ds_read_b128 v[202:205], v155 offset:53248
	ds_read_b128 v[206:209], v155 offset:54272
	ds_read_b128 v[210:213], v155 offset:55296
	ds_read_b128 v[214:217], v155 offset:56320
	s_waitcnt vmcnt(8)
	s_waitcnt lgkmcnt(0)
	s_barrier
	s_setprio 0
	s_waitcnt lgkmcnt(0)
	v_mfma_f32_16x16x32_bf16 v[60:63], v[144:147], v[186:189], v[60:63]
	v_mfma_f32_16x16x32_bf16 v[56:59], v[162:165], v[186:189], v[56:59]
	v_mfma_f32_16x16x32_bf16 v[44:47], v[144:147], v[194:197], v[44:47]
	v_mfma_f32_16x16x32_bf16 v[40:43], v[162:165], v[194:197], v[40:43]
	v_mfma_f32_16x16x32_bf16 v[28:31], v[144:147], v[202:205], v[28:31]
	v_mfma_f32_16x16x32_bf16 v[24:27], v[162:165], v[202:205], v[24:27]
	v_mfma_f32_16x16x32_bf16 v[12:15], v[144:147], v[210:213], v[12:15]
	v_mfma_f32_16x16x32_bf16 v[8:11], v[162:165], v[210:213], v[8:11]
	v_mfma_f32_16x16x32_bf16 v[60:63], v[158:161], v[190:193], v[60:63]
	v_mfma_f32_16x16x32_bf16 v[56:59], v[166:169], v[190:193], v[56:59]
	v_mfma_f32_16x16x32_bf16 v[44:47], v[158:161], v[198:201], v[44:47]
	v_mfma_f32_16x16x32_bf16 v[40:43], v[166:169], v[198:201], v[40:43]
	v_mfma_f32_16x16x32_bf16 v[28:31], v[158:161], v[206:209], v[28:31]
	v_mfma_f32_16x16x32_bf16 v[24:27], v[166:169], v[206:209], v[24:27]
	v_mfma_f32_16x16x32_bf16 v[12:15], v[158:161], v[214:217], v[12:15]
	v_mfma_f32_16x16x32_bf16 v[8:11], v[166:169], v[214:217], v[8:11]
	v_mfma_f32_16x16x32_bf16 v[52:55], v[170:173], v[186:189], v[52:55]
	v_mfma_f32_16x16x32_bf16 v[48:51], v[178:181], v[186:189], v[48:51]
	v_mfma_f32_16x16x32_bf16 v[36:39], v[170:173], v[194:197], v[36:39]
	v_mfma_f32_16x16x32_bf16 v[32:35], v[178:181], v[194:197], v[32:35]
	v_mfma_f32_16x16x32_bf16 v[20:23], v[170:173], v[202:205], v[20:23]
	v_mfma_f32_16x16x32_bf16 v[16:19], v[178:181], v[202:205], v[16:19]
	v_mfma_f32_16x16x32_bf16 v[4:7], v[170:173], v[210:213], v[4:7]
	v_mfma_f32_16x16x32_bf16 v[0:3], v[178:181], v[210:213], v[0:3]
	v_mfma_f32_16x16x32_bf16 v[52:55], v[174:177], v[190:193], v[52:55]
	v_mfma_f32_16x16x32_bf16 v[48:51], v[182:185], v[190:193], v[48:51]
	v_mfma_f32_16x16x32_bf16 v[36:39], v[174:177], v[198:201], v[36:39]
	v_mfma_f32_16x16x32_bf16 v[32:35], v[182:185], v[198:201], v[32:35]
	v_mfma_f32_16x16x32_bf16 v[20:23], v[174:177], v[206:209], v[20:23]
	v_mfma_f32_16x16x32_bf16 v[16:19], v[182:185], v[206:209], v[16:19]
	v_mfma_f32_16x16x32_bf16 v[4:7], v[174:177], v[214:217], v[4:7]
	v_mfma_f32_16x16x32_bf16 v[0:3], v[182:185], v[214:217], v[0:3]
	s_setprio 1
	s_barrier
	s_add_i32 s61, s61, 2
	s_add_u32 s59, s59, 0x100
	s_addc_u32 s60, s60, 0
	s_cmp_gt_u32 s61, 29
	s_mov_b64 s[38:39], s[40:41]
	s_cbranch_scc0 .LBB0_1240
	s_setprio 0
	s_and_b64 vcc, exec, s[6:7]
	s_cbranch_vccz .LBB0_1243
	s_barrier

.LBB0_1327:
	ds_read_b128 v[144:147], v151
	ds_read_b128 v[154:157], v151 offset:1024
	ds_read_b128 v[158:161], v151 offset:2048
	ds_read_b128 v[162:165], v151 offset:3072
	ds_read_b128 v[166:169], v152
	ds_read_b128 v[170:173], v152 offset:1024
	ds_read_b128 v[174:177], v152 offset:2048
	ds_read_b128 v[178:181], v152 offset:3072
	s_add_u32 s34, s30, 0x100
	s_addc_u32 s35, s31, 0
	s_cmpk_eq_i32 s55, 0x54
	s_cselect_b32 s39, s5, s35
	s_cselect_b32 s38, s4, s34
	s_cselect_b32 s37, s29, s54
	s_cselect_b32 s36, s28, s53
	v_lshl_add_u64 v[182:183], s[30:31], 0, v[136:137]
	s_add_i32 m0, s40, 0xc000
	s_nop 0
	global_load_lds_dwordx4 v[182:183], off
	v_lshl_add_u64 v[182:183], s[30:31], 0, v[138:139]
	s_add_i32 m0, s40, 0xe000
	s_nop 0
	global_load_lds_dwordx4 v[182:183], off
	ds_read_b128 v[182:185], v153
	ds_read_b128 v[186:189], v153 offset:1024
	ds_read_b128 v[190:193], v153 offset:2048
	ds_read_b128 v[194:197], v153 offset:3072
	ds_read_b128 v[198:201], v153 offset:4096
	ds_read_b128 v[202:205], v153 offset:5120
	ds_read_b128 v[206:209], v153 offset:6144
	ds_read_b128 v[210:213], v153 offset:7168
	s_waitcnt vmcnt(8)
	s_waitcnt lgkmcnt(0)
	s_barrier
	s_setprio 0
	s_waitcnt lgkmcnt(0)
	v_mfma_f32_16x16x32_bf16 v[124:127], v[144:147], v[182:185], v[124:127]
	v_mfma_f32_16x16x32_bf16 v[120:123], v[158:161], v[182:185], v[120:123]
	v_mfma_f32_16x16x32_bf16 v[108:111], v[144:147], v[190:193], v[108:111]
	v_mfma_f32_16x16x32_bf16 v[104:107], v[158:161], v[190:193], v[104:107]
	v_mfma_f32_16x16x32_bf16 v[92:95], v[144:147], v[198:201], v[92:95]
	v_mfma_f32_16x16x32_bf16 v[88:91], v[158:161], v[198:201], v[88:91]
	v_mfma_f32_16x16x32_bf16 v[76:79], v[144:147], v[206:209], v[76:79]
	v_mfma_f32_16x16x32_bf16 v[72:75], v[158:161], v[206:209], v[72:75]
	v_mfma_f32_16x16x32_bf16 v[124:127], v[154:157], v[186:189], v[124:127]
	v_mfma_f32_16x16x32_bf16 v[120:123], v[162:165], v[186:189], v[120:123]
	v_mfma_f32_16x16x32_bf16 v[108:111], v[154:157], v[194:197], v[108:111]
	v_mfma_f32_16x16x32_bf16 v[104:107], v[162:165], v[194:197], v[104:107]
	v_mfma_f32_16x16x32_bf16 v[92:95], v[154:157], v[202:205], v[92:95]
	v_mfma_f32_16x16x32_bf16 v[88:91], v[162:165], v[202:205], v[88:91]
	v_mfma_f32_16x16x32_bf16 v[76:79], v[154:157], v[210:213], v[76:79]
	v_mfma_f32_16x16x32_bf16 v[72:75], v[162:165], v[210:213], v[72:75]
	v_mfma_f32_16x16x32_bf16 v[116:119], v[166:169], v[182:185], v[116:119]
	v_mfma_f32_16x16x32_bf16 v[112:115], v[174:177], v[182:185], v[112:115]
	v_mfma_f32_16x16x32_bf16 v[100:103], v[166:169], v[190:193], v[100:103]
	v_mfma_f32_16x16x32_bf16 v[96:99], v[174:177], v[190:193], v[96:99]
	v_mfma_f32_16x16x32_bf16 v[84:87], v[166:169], v[198:201], v[84:87]
	v_mfma_f32_16x16x32_bf16 v[80:83], v[174:177], v[198:201], v[80:83]
	v_mfma_f32_16x16x32_bf16 v[68:71], v[166:169], v[206:209], v[68:71]
	v_mfma_f32_16x16x32_bf16 v[64:67], v[174:177], v[206:209], v[64:67]
	v_mfma_f32_16x16x32_bf16 v[116:119], v[170:173], v[186:189], v[116:119]
	v_mfma_f32_16x16x32_bf16 v[112:115], v[178:181], v[186:189], v[112:115]
	v_mfma_f32_16x16x32_bf16 v[100:103], v[170:173], v[194:197], v[100:103]
	v_mfma_f32_16x16x32_bf16 v[96:99], v[178:181], v[194:197], v[96:99]
	v_mfma_f32_16x16x32_bf16 v[84:87], v[170:173], v[202:205], v[84:87]
	v_mfma_f32_16x16x32_bf16 v[80:83], v[178:181], v[202:205], v[80:83]
	v_mfma_f32_16x16x32_bf16 v[68:71], v[170:173], v[210:213], v[68:71]
	v_mfma_f32_16x16x32_bf16 v[64:67], v[178:181], v[210:213], v[64:67]
	s_setprio 1
	s_barrier
	s_add_i32 s30, s48, s23
	v_lshl_add_u64 v[214:215], s[36:37], 0, v[130:131]
	s_mov_b32 m0, s30
	v_lshl_add_u64 v[216:217], s[36:37], 0, v[134:135]
	global_load_lds_dwordx4 v[214:215], off
	s_add_i32 m0, s30, 0x2000
	s_add_u32 s30, s36, 0x160000
	s_addc_u32 s31, s37, 0
	s_add_i32 s56, s49, s23
	global_load_lds_dwordx4 v[216:217], off
	v_lshl_add_u64 v[182:183], s[30:31], 0, v[130:131]
	s_mov_b32 m0, s56
	v_lshl_add_u64 v[218:219], s[38:39], 0, v[128:129]
	global_load_lds_dwordx4 v[182:183], off
	v_lshl_add_u64 v[182:183], s[30:31], 0, v[134:135]
	s_add_i32 m0, s56, 0x2000
	v_lshl_add_u64 v[220:221], s[38:39], 0, v[132:133]
	global_load_lds_dwordx4 v[182:183], off
	s_mov_b32 m0, s40
	s_nop 0
	global_load_lds_dwordx4 v[218:219], off
	s_mov_b32 m0, s41
	s_nop 0
	global_load_lds_dwordx4 v[220:221], off
	ds_read_b128 v[182:185], v153 offset:16384
	ds_read_b128 v[186:189], v153 offset:17408
	ds_read_b128 v[190:193], v153 offset:18432
	ds_read_b128 v[194:197], v153 offset:19456
	ds_read_b128 v[198:201], v153 offset:20480
	ds_read_b128 v[202:205], v153 offset:21504
	ds_read_b128 v[206:209], v153 offset:22528
	ds_read_b128 v[210:213], v153 offset:23552
	s_waitcnt vmcnt(8)
	s_waitcnt lgkmcnt(0)
	s_barrier
	s_setprio 0
	s_waitcnt lgkmcnt(0)
	v_mfma_f32_16x16x32_bf16 v[60:63], v[144:147], v[182:185], v[60:63]
	v_mfma_f32_16x16x32_bf16 v[56:59], v[158:161], v[182:185], v[56:59]
	v_mfma_f32_16x16x32_bf16 v[44:47], v[144:147], v[190:193], v[44:47]
	v_mfma_f32_16x16x32_bf16 v[40:43], v[158:161], v[190:193], v[40:43]
	v_mfma_f32_16x16x32_bf16 v[28:31], v[144:147], v[198:201], v[28:31]
	v_mfma_f32_16x16x32_bf16 v[24:27], v[158:161], v[198:201], v[24:27]
	v_mfma_f32_16x16x32_bf16 v[12:15], v[144:147], v[206:209], v[12:15]
	v_mfma_f32_16x16x32_bf16 v[8:11], v[158:161], v[206:209], v[8:11]
	v_mfma_f32_16x16x32_bf16 v[60:63], v[154:157], v[186:189], v[60:63]
	v_mfma_f32_16x16x32_bf16 v[56:59], v[162:165], v[186:189], v[56:59]
	v_mfma_f32_16x16x32_bf16 v[44:47], v[154:157], v[194:197], v[44:47]
	v_mfma_f32_16x16x32_bf16 v[40:43], v[162:165], v[194:197], v[40:43]
	v_mfma_f32_16x16x32_bf16 v[28:31], v[154:157], v[202:205], v[28:31]
	v_mfma_f32_16x16x32_bf16 v[24:27], v[162:165], v[202:205], v[24:27]
	v_mfma_f32_16x16x32_bf16 v[12:15], v[154:157], v[210:213], v[12:15]
	v_mfma_f32_16x16x32_bf16 v[8:11], v[162:165], v[210:213], v[8:11]
	v_mfma_f32_16x16x32_bf16 v[52:55], v[166:169], v[182:185], v[52:55]
	v_mfma_f32_16x16x32_bf16 v[48:51], v[174:177], v[182:185], v[48:51]
	v_mfma_f32_16x16x32_bf16 v[36:39], v[166:169], v[190:193], v[36:39]
	v_mfma_f32_16x16x32_bf16 v[32:35], v[174:177], v[190:193], v[32:35]
	v_mfma_f32_16x16x32_bf16 v[20:23], v[166:169], v[198:201], v[20:23]
	v_mfma_f32_16x16x32_bf16 v[16:19], v[174:177], v[198:201], v[16:19]
	v_mfma_f32_16x16x32_bf16 v[4:7], v[166:169], v[206:209], v[4:7]
	v_mfma_f32_16x16x32_bf16 v[0:3], v[174:177], v[206:209], v[0:3]
	v_mfma_f32_16x16x32_bf16 v[52:55], v[170:173], v[186:189], v[52:55]
	v_mfma_f32_16x16x32_bf16 v[48:51], v[178:181], v[186:189], v[48:51]
	v_mfma_f32_16x16x32_bf16 v[36:39], v[170:173], v[194:197], v[36:39]
	v_mfma_f32_16x16x32_bf16 v[32:35], v[178:181], v[194:197], v[32:35]
	v_mfma_f32_16x16x32_bf16 v[20:23], v[170:173], v[202:205], v[20:23]
	v_mfma_f32_16x16x32_bf16 v[16:19], v[178:181], v[202:205], v[16:19]
	v_mfma_f32_16x16x32_bf16 v[4:7], v[170:173], v[210:213], v[4:7]
	v_mfma_f32_16x16x32_bf16 v[0:3], v[178:181], v[210:213], v[0:3]
	s_setprio 1
	s_barrier
	s_add_i32 s56, 0, 0x18000
	s_add_i32 s57, 0, 0x1c000
	v_add_u32_e32 v162, s56, v148
	v_add_u32_e32 v178, s57, v148
	ds_read_b128 v[144:147], v162
	ds_read_b128 v[154:157], v162 offset:1024
	ds_read_b128 v[158:161], v162 offset:2048
	ds_read_b128 v[162:165], v162 offset:3072
	ds_read_b128 v[166:169], v178
	ds_read_b128 v[170:173], v178 offset:1024
	ds_read_b128 v[174:177], v178 offset:2048
	ds_read_b128 v[178:181], v178 offset:3072
	s_add_u32 s30, s38, 0x160000
	s_addc_u32 s31, s39, 0
	s_mov_b32 m0, s42
	v_lshl_add_u64 v[182:183], s[30:31], 0, v[128:129]
	global_load_lds_dwordx4 v[182:183], off
	v_lshl_add_u64 v[182:183], s[30:31], 0, v[132:133]
	s_mov_b32 m0, s43
	s_nop 0
	global_load_lds_dwordx4 v[182:183], off
	ds_read_b128 v[182:185], v153 offset:32768
	ds_read_b128 v[186:189], v153 offset:33792
	ds_read_b128 v[190:193], v153 offset:34816
	ds_read_b128 v[194:197], v153 offset:35840
	ds_read_b128 v[198:201], v153 offset:36864
	ds_read_b128 v[202:205], v153 offset:37888
	ds_read_b128 v[206:209], v153 offset:38912
	ds_read_b128 v[210:213], v153 offset:39936
	s_waitcnt vmcnt(8)
	s_waitcnt lgkmcnt(0)
	s_barrier
	s_setprio 0
	s_waitcnt lgkmcnt(0)
	v_mfma_f32_16x16x32_bf16 v[124:127], v[144:147], v[182:185], v[124:127]
	v_mfma_f32_16x16x32_bf16 v[120:123], v[158:161], v[182:185], v[120:123]
	v_mfma_f32_16x16x32_bf16 v[108:111], v[144:147], v[190:193], v[108:111]
	v_mfma_f32_16x16x32_bf16 v[104:107], v[158:161], v[190:193], v[104:107]
	v_mfma_f32_16x16x32_bf16 v[92:95], v[144:147], v[198:201], v[92:95]
	v_mfma_f32_16x16x32_bf16 v[88:91], v[158:161], v[198:201], v[88:91]
	v_mfma_f32_16x16x32_bf16 v[76:79], v[144:147], v[206:209], v[76:79]
	v_mfma_f32_16x16x32_bf16 v[72:75], v[158:161], v[206:209], v[72:75]
	v_mfma_f32_16x16x32_bf16 v[124:127], v[154:157], v[186:189], v[124:127]
	v_mfma_f32_16x16x32_bf16 v[120:123], v[162:165], v[186:189], v[120:123]
	v_mfma_f32_16x16x32_bf16 v[108:111], v[154:157], v[194:197], v[108:111]
	v_mfma_f32_16x16x32_bf16 v[104:107], v[162:165], v[194:197], v[104:107]
	v_mfma_f32_16x16x32_bf16 v[92:95], v[154:157], v[202:205], v[92:95]
	v_mfma_f32_16x16x32_bf16 v[88:91], v[162:165], v[202:205], v[88:91]
	v_mfma_f32_16x16x32_bf16 v[76:79], v[154:157], v[210:213], v[76:79]
	v_mfma_f32_16x16x32_bf16 v[72:75], v[162:165], v[210:213], v[72:75]
	v_mfma_f32_16x16x32_bf16 v[116:119], v[166:169], v[182:185], v[116:119]
	v_mfma_f32_16x16x32_bf16 v[112:115], v[174:177], v[182:185], v[112:115]
	v_mfma_f32_16x16x32_bf16 v[100:103], v[166:169], v[190:193], v[100:103]
	v_mfma_f32_16x16x32_bf16 v[96:99], v[174:177], v[190:193], v[96:99]
	v_mfma_f32_16x16x32_bf16 v[84:87], v[166:169], v[198:201], v[84:87]
	v_mfma_f32_16x16x32_bf16 v[80:83], v[174:177], v[198:201], v[80:83]
	v_mfma_f32_16x16x32_bf16 v[68:71], v[166:169], v[206:209], v[68:71]
	v_mfma_f32_16x16x32_bf16 v[64:67], v[174:177], v[206:209], v[64:67]
	v_mfma_f32_16x16x32_bf16 v[116:119], v[170:173], v[186:189], v[116:119]
	v_mfma_f32_16x16x32_bf16 v[112:115], v[178:181], v[186:189], v[112:115]
	v_mfma_f32_16x16x32_bf16 v[100:103], v[170:173], v[194:197], v[100:103]
	v_mfma_f32_16x16x32_bf16 v[96:99], v[178:181], v[194:197], v[96:99]
	v_mfma_f32_16x16x32_bf16 v[84:87], v[170:173], v[202:205], v[84:87]
	v_mfma_f32_16x16x32_bf16 v[80:83], v[178:181], v[202:205], v[80:83]
	v_mfma_f32_16x16x32_bf16 v[68:71], v[170:173], v[210:213], v[68:71]
	v_mfma_f32_16x16x32_bf16 v[64:67], v[178:181], v[210:213], v[64:67]
	s_setprio 1
	s_barrier
	s_add_i32 s30, s56, s23
	v_lshl_add_u64 v[182:183], v[214:215], 0, s[16:17]
	s_mov_b32 m0, s30
	s_nop 0
	global_load_lds_dwordx4 v[182:183], off
	s_add_i32 m0, s30, 0x2000
	s_add_u32 s30, s36, 0x160080
	v_lshl_add_u64 v[182:183], v[216:217], 0, s[16:17]
	s_addc_u32 s31, s37, 0
	s_add_i32 s36, s57, s23
	global_load_lds_dwordx4 v[182:183], off
	v_lshl_add_u64 v[182:183], s[30:31], 0, v[130:131]
	s_mov_b32 m0, s36
	s_nop 0
	global_load_lds_dwordx4 v[182:183], off
	v_lshl_add_u64 v[182:183], s[30:31], 0, v[134:135]
	s_add_i32 m0, s36, 0x2000
	s_nop 0
	global_load_lds_dwordx4 v[182:183], off
	v_lshl_add_u64 v[182:183], v[218:219], 0, s[16:17]
	s_mov_b32 m0, s45
	s_nop 0
	global_load_lds_dwordx4 v[182:183], off
	v_lshl_add_u64 v[182:183], v[220:221], 0, s[16:17]
	s_mov_b32 m0, s46
	s_nop 0
	global_load_lds_dwordx4 v[182:183], off
	ds_read_b128 v[182:185], v153 offset:49152
	ds_read_b128 v[186:189], v153 offset:50176
	ds_read_b128 v[190:193], v153 offset:51200
	ds_read_b128 v[194:197], v153 offset:52224
	ds_read_b128 v[198:201], v153 offset:53248
	ds_read_b128 v[202:205], v153 offset:54272
	ds_read_b128 v[206:209], v153 offset:55296
	ds_read_b128 v[210:213], v153 offset:56320
	s_waitcnt vmcnt(8)
	s_waitcnt lgkmcnt(0)
	s_barrier
	s_setprio 0
	s_waitcnt lgkmcnt(0)
	v_mfma_f32_16x16x32_bf16 v[60:63], v[144:147], v[182:185], v[60:63]
	v_mfma_f32_16x16x32_bf16 v[56:59], v[158:161], v[182:185], v[56:59]
	v_mfma_f32_16x16x32_bf16 v[44:47], v[144:147], v[190:193], v[44:47]
	v_mfma_f32_16x16x32_bf16 v[40:43], v[158:161], v[190:193], v[40:43]
	v_mfma_f32_16x16x32_bf16 v[28:31], v[144:147], v[198:201], v[28:31]
	v_mfma_f32_16x16x32_bf16 v[24:27], v[158:161], v[198:201], v[24:27]
	v_mfma_f32_16x16x32_bf16 v[12:15], v[144:147], v[206:209], v[12:15]
	v_mfma_f32_16x16x32_bf16 v[8:11], v[158:161], v[206:209], v[8:11]
	v_mfma_f32_16x16x32_bf16 v[60:63], v[154:157], v[186:189], v[60:63]
	v_mfma_f32_16x16x32_bf16 v[56:59], v[162:165], v[186:189], v[56:59]
	v_mfma_f32_16x16x32_bf16 v[44:47], v[154:157], v[194:197], v[44:47]
	v_mfma_f32_16x16x32_bf16 v[40:43], v[162:165], v[194:197], v[40:43]
	v_mfma_f32_16x16x32_bf16 v[28:31], v[154:157], v[202:205], v[28:31]
	v_mfma_f32_16x16x32_bf16 v[24:27], v[162:165], v[202:205], v[24:27]
	v_mfma_f32_16x16x32_bf16 v[12:15], v[154:157], v[210:213], v[12:15]
	v_mfma_f32_16x16x32_bf16 v[8:11], v[162:165], v[210:213], v[8:11]
	v_mfma_f32_16x16x32_bf16 v[52:55], v[166:169], v[182:185], v[52:55]
	v_mfma_f32_16x16x32_bf16 v[48:51], v[174:177], v[182:185], v[48:51]
	v_mfma_f32_16x16x32_bf16 v[36:39], v[166:169], v[190:193], v[36:39]
	v_mfma_f32_16x16x32_bf16 v[32:35], v[174:177], v[190:193], v[32:35]
	v_mfma_f32_16x16x32_bf16 v[20:23], v[166:169], v[198:201], v[20:23]
	v_mfma_f32_16x16x32_bf16 v[16:19], v[174:177], v[198:201], v[16:19]
	v_mfma_f32_16x16x32_bf16 v[4:7], v[166:169], v[206:209], v[4:7]
	v_mfma_f32_16x16x32_bf16 v[0:3], v[174:177], v[206:209], v[0:3]
	v_mfma_f32_16x16x32_bf16 v[52:55], v[170:173], v[186:189], v[52:55]
	v_mfma_f32_16x16x32_bf16 v[48:51], v[178:181], v[186:189], v[48:51]
	v_mfma_f32_16x16x32_bf16 v[36:39], v[170:173], v[194:197], v[36:39]
	v_mfma_f32_16x16x32_bf16 v[32:35], v[178:181], v[194:197], v[32:35]
	v_mfma_f32_16x16x32_bf16 v[20:23], v[170:173], v[202:205], v[20:23]
	v_mfma_f32_16x16x32_bf16 v[16:19], v[178:181], v[202:205], v[16:19]
	v_mfma_f32_16x16x32_bf16 v[4:7], v[170:173], v[210:213], v[4:7]
	v_mfma_f32_16x16x32_bf16 v[0:3], v[178:181], v[210:213], v[0:3]
	s_setprio 1
	s_barrier
	s_add_i32 s55, s55, 2
	s_add_u32 s53, s53, 0x100
	s_addc_u32 s54, s54, 0
	s_cmpk_gt_u32 s55, 0x55
	s_mov_b64 s[30:31], s[34:35]
	s_cbranch_scc0 .LBB0_1327
	s_setprio 0
	s_and_b64 vcc, exec, s[8:9]
	s_cbranch_vccz .LBB0_1330
	s_barrier
